# attention tile loop rewritten by hand: software-pipelined (QK(t) with sum/pack of t-1, PV(t-1) with exp(t)), low-instruction-count hot loops for mask-free tiles
# speedup vs baseline: 1.0275x; 1.0240x over previous
; #define DMA_TILE(Kp, Vp, slot) do { \
;         glds16((Kp) + kofs, (unsigned)__builtin_amdgcn_readfirstlane((int)(lds_base + (unsigned)((slot) * ATT_BUF + w * 1024)))); \
;         glds16((Vp) + vofs, (unsigned)__builtin_amdgcn_readfirstlane((int)(lds_base + (unsigned)((slot) * ATT_BUF + LDS_VT + w * 1024)))); } while (0)
; #define WAIT_VM(n) asm volatile("s_waitcnt vmcnt(" #n ")" ::: "memory")
; #define LBAR() do { asm volatile("s_waitcnt lgkmcnt(0)" ::: "memory"); __builtin_amdgcn_s_barrier(); asm volatile("" ::: "memory"); } while (0)
; #define TILE_SRC(ii, kp, vp) do { const int jn_ = LIST[(ii)]; const bool ns_ = (ii) < nsel; kp = KS + (ns_ ? (size_t)0 : 2 * KV_SLOT) + (size_t)jn_ * 4096; vp = kp + KV_SLOT; } while (0)
; DI void attn_unit(LAS unsigned char* lds, const Args& a, int bg, int qt) {
;     ...
;     const unsigned mask_q = two_cmp ? MSK[qloc] : causal_all;
;     const int nsel = LIST[64], ntile = LIST[65];
;     ...
;     if (ntile > 1) { const bf16_t* kp; const bf16_t* vp; TILE_SRC(1, kp, vp); DMA_TILE(kp, vp, 3); }
;     if (ntile > 2) { const bf16_t* kp; const bf16_t* vp; TILE_SRC(2, kp, vp); DMA_TILE(kp, vp, 0); }
;     for (int i = 0; i < ntile; ++i) {
;         const int j = LIST[i]; const bool is_sel = i < nsel;
;         if (i + 2 < ntile) WAIT_VM(4); else if (i + 1 < ntile) WAIT_VM(2); else WAIT_VM(0);
;         LBAR();
;         if (i + 3 < ntile) { const bf16_t* kp; const bf16_t* vp; TILE_SRC(i + 3, kp, vp); DMA_TILE(kp, vp, (i + 1) & 3); }
.LBB0_778:
	s_mov_b32 s29, m0
	v_mov_b32_e32 v242, 0xff800000
	v_lshrrev_b32_e32 v243, 5, v146
	v_lshlrev_b32_e32 v243, 2, v243
	v_add_u32_e32 v240, v187, v188
	v_add_u32_e32 v241, v189, v185
	v_add3_u32 v241, v241, v190, v191
	v_mov_b32_e32 v248, v100
	v_mov_b32_e32 v249, 0
	v_mov_b32_e32 v250, v150
	v_mov_b32_e32 v251, 0
	v_mov_b32_e32 v252, v137
	v_mov_b32_e32 v253, v139
	v_lshl_add_u64 v[186:187], s[54:55], 0, v[248:249]
	v_lshl_add_u64 v[188:189], s[54:55], 0, v[250:251]
	s_mov_b32 s77, 0
	s_add_i32 s70, s71, -12
	s_mov_b32 s101, 0
	s_mov_b32 s100, s19
	s_add_i32 s67, s19, -3
	s_mov_b32 s68, 0
	s_mov_b32 s4, 0
	s_cmp_lt_u32 s73, 16
	s_cselect_b32 s69, 1, 0
	v_lshl_add_u64 v[188:189], v[188:189], 0, s[50:51]
	v_mov_b32_e32 v116, s70
	ds_read2_b32 v[254:255], v116 offset1:2
	s_waitcnt lgkmcnt(0)
	v_readfirstlane_b32 s98, v254
	v_readfirstlane_b32 s99, v255
.Lat_first:
	s_add_i32 s8, s77, 1
	s_cmp_lt_i32 s8, s18
	s_cbranch_scc0 .Lat_w0_1
	s_cmp_eq_u32 s77, 0
	s_cbranch_scc0 .Lat_w2_2
	s_cmp_gt_i32 s18, 2
	s_cbranch_scc0 .Lat_w2_2
	s_waitcnt vmcnt(4)
	s_branch .Lat_wd_3
.Lat_w2_2:
	s_waitcnt vmcnt(2)
	s_branch .Lat_wd_3

; DI void attn_tile(LAS const unsigned char* Ks, LAS const unsigned char* VT, const bf16x8 (&qf)[4], int ql, int hi,
;                   bool need_mask, bool col_en, int lo_b, int hi_b, float& m_ref, float& l_run, f32x16 (&o)[2], f32x16 (&sp)[2]) {
;     const int lane_ = ql + 32 * hi;
;     const float bias = col_en ? -m_ref : -INFINITY;
;     const bool plain = __all(col_en && (m_ref == 0.f));
; #pragma unroll
;     for (int p = 0; p < 2; ++p) {
;         bf16x8 kf[4];
; #pragma unroll
;         for (int d0 = 0; d0 < 4; ++d0) { const int c = 2 * d0 + hi; kf[d0] = *(LAS const bf16x8*)(Ks + c * 1024 + ((ql + 32 * p) << 4)); }
;         f32x16 acc;
;         if (plain) {
; #pragma unroll
;             for (int r = 0; r < 16; ++r) acc[r] = 0.f;
; #pragma unroll
;             for (int d0 = 0; d0 < 4; ++d0) acc = MFMA32(kf[d0], qf[d0], acc);
;         } else {
; #pragma unroll
;             for (int r = 0; r < 16; ++r) acc[r] = bias;
; #pragma unroll
;             for (int d0 = 0; d0 < 4; ++d0) acc = MFMA32(kf[d0], qf[d0], acc);
;         }
;         sp[p] = acc;
;     }
;     if (need_mask) {
; #pragma unroll
;         for (int p = 0; p < 2; ++p)
; #pragma unroll
;             for (int r = 0; r < 16; ++r) { const int kvl = 32 * p + (r & 3) + 8 * (r >> 2) + 4 * hi; const bool ok = (kvl <= hi_b) && (kvl > lo_b); sp[p][r] = ok ? sp[p][r] : -INFINITY; }
; DI void attn_unit(LAS unsigned char* lds, const Args& a, int bg, int qt) {
;     ...
;     for (int i = 0; i < ntile; ++i) {
;         const int j = LIST[i]; const bool is_sel = i < nsel;
;         if (i + 2 < ntile) WAIT_VM(4); else if (i + 1 < ntile) WAIT_VM(2); else WAIT_VM(0);
;         LBAR();
;         if (i + 3 < ntile) { const bf16_t* kp; const bf16_t* vp; TILE_SRC(i + 3, kp, vp); DMA_TILE(kp, vp, (i + 1) & 3); }
;         if (i == nsel) {
;             const float lt = half_sum(l_run); const float gi = GT[512] / lt;
; #pragma unroll
;             for (int r = 0; r < 16; ++r) { oacc[0][r] += gi * o[0][r]; oacc[1][r] += gi * o[1][r]; o[0][r] = 0.f; o[1][r] = 0.f; }
;             m_ref = 0.f; l_run = 0.f;
;         }
;         bool need_mask, col_en = true; int lo_b = -1, hi_b = 63;
;         if (is_sel) { need_mask = (j == qt); if (j == qt) hi_b = qloc; col_en = ((mask_q >> j) & 1u) != 0u; }
;         else { need_mask = (j == qt) || (j == qt - 8); if (j == qt) hi_b = qloc; if (j == qt - 8) lo_b = qloc; }
.Lat_wd_3:
	s_waitcnt lgkmcnt(0)
	s_barrier
	s_lshl2_add_u32 s78, s77, s70
	s_add_i32 s79, s77, 2
	s_and_b32 s79, s79, 3
	s_lshl_b32 s79, s79, 14
	s_cmp_lt_i32 s77, 1
	s_cbranch_scc1 .Lat_nodma_4
	s_add_i32 s8, s77, 2
	s_cmp_ge_i32 s8, s18
	s_cbranch_scc1 .Lat_nodma_4
	s_cmp_lt_i32 s8, s19
	s_cselect_b32 s9, 0, 0x2000000
	s_lshl_b32 s10, s99, 13
	s_add_u32 s10, s10, s9
	s_add_u32 s8, s54, s10
	s_addc_u32 s9, s55, 0
	s_and_b32 s11, s77, 3
	s_lshl_b32 s11, s11, 14
	s_add_i32 s11, s11, s75
	v_lshl_add_u64 v[122:123], s[8:9], 0, v[248:249]
	v_lshl_add_u64 v[124:125], s[8:9], 0, v[250:251]
	s_mov_b32 m0, s11
	v_lshl_add_u64 v[124:125], v[124:125], 0, s[50:51]
	global_load_lds_dwordx4 v[122:123], off
	s_add_i32 m0, s11, 0x2000
	s_nop 0
	global_load_lds_dwordx4 v[124:125], off
.Lat_nodma_4:
	v_add_u32_e32 v246, s79, v240
	v_mov_b32_e32 v116, s78
	ds_read_b128 v[84:87], v246
	ds_read_b128 v[88:91], v246 offset:2048
	ds_read_b128 v[92:95], v246 offset:4096
	ds_read_b128 v[96:99], v246 offset:6144
	ds_read_b128 v[100:103], v246 offset:512
	ds_read_b128 v[104:107], v246 offset:2560
	ds_read_b128 v[108:111], v246 offset:4608
	ds_read_b128 v[112:115], v246 offset:6656
	ds_read2_b32 v[254:255], v116 offset0:1 offset1:3
	s_mov_b64 s[12:13], exec
	s_mov_b32 s28, 1
	s_cmp_lt_i32 s77, s19
	s_cselect_b32 s6, 1, 0
	s_cbranch_scc0 .Lat_nosel_5
	v_lshrrev_b32_e32 v247, s98, v252
	v_and_b32_e32 v247, 1, v247
	v_cmp_eq_u32_e64 s[12:13], 1, v247
	s_nop 3
	s_cmp_eq_u64 s[12:13], exec
	s_cselect_b32 s28, 1, 0
.Lat_nosel_5:
	s_cmp_eq_u32 s98, s73
	s_cselect_b32 s8, 1, 0
	s_cmp_eq_u32 s98, s20
	s_cselect_b32 s9, 1, 0
	s_andn2_b32 s9, s9, s6
	s_or_b32 s5, s8, s9
	s_cmp_eq_u32 s5, 0
	s_cbranch_scc1 .Lat_nomask_6
	v_mov_b32_e32 v120, 63
	v_mov_b32_e32 v121, -1
	s_cmp_eq_u32 s8, 1
	s_cselect_b64 s[10:11], -1, 0
	s_cmp_eq_u32 s9, 1
	s_cselect_b64 s[8:9], -1, 0
	v_cndmask_b32_e64 v120, v120, v253, s[10:11]
	v_cndmask_b32_e64 v121, v121, v253, s[8:9]
	v_sub_u32_e32 v120, v120, v243
	v_sub_u32_e32 v121, v121, v243
.Lat_nomask_6:
	v_cmp_eq_f32_e32 vcc, 0, v143
	s_mov_b32 s7, 1
	s_nop 1
	s_cmp_eq_u64 vcc, exec
	s_cbranch_scc1 .Lat_qkgo_8
	s_mov_b32 s7, 0
	s_mov_b32 s68, 1
	v_xor_b32_e32 v244, 0x80000000, v143
	v_mov_b32_e32 v50, v244
	v_mov_b32_e32 v34, v244
	v_mov_b32_e32 v51, v244
	v_mov_b32_e32 v35, v244
	v_mov_b32_e32 v52, v244
	v_mov_b32_e32 v36, v244
	v_mov_b32_e32 v53, v244
	v_mov_b32_e32 v37, v244
	v_mov_b32_e32 v54, v244
	v_mov_b32_e32 v38, v244
	v_mov_b32_e32 v55, v244
	v_mov_b32_e32 v39, v244
	v_mov_b32_e32 v56, v244
	v_mov_b32_e32 v40, v244
	v_mov_b32_e32 v57, v244
	v_mov_b32_e32 v41, v244
	v_mov_b32_e32 v58, v244
	v_mov_b32_e32 v42, v244
	v_mov_b32_e32 v59, v244
	v_mov_b32_e32 v43, v244
	v_mov_b32_e32 v60, v244
	v_mov_b32_e32 v44, v244
	v_mov_b32_e32 v61, v244
	v_mov_b32_e32 v45, v244
	v_mov_b32_e32 v62, v244
	v_mov_b32_e32 v46, v244
	v_mov_b32_e32 v63, v244
	v_mov_b32_e32 v47, v244
	v_mov_b32_e32 v64, v244
	v_mov_b32_e32 v48, v244
	v_mov_b32_e32 v65, v244
	v_mov_b32_e32 v49, v244
	s_nop 1
.Lat_qkgo_8:
	s_waitcnt lgkmcnt(8)
	s_cmp_eq_u32 s7, 1
	s_cbranch_scc0 .Lat_c0s_9
	v_mfma_f32_32x32x16_bf16 v[50:65], v[84:87], v[66:69], 0
	s_branch .Lat_c0j_10
.Lat_c0s_9:
	v_mfma_f32_32x32x16_bf16 v[50:65], v[84:87], v[66:69], v[50:65]
.Lat_c0j_10:
	s_waitcnt lgkmcnt(7)
	v_mfma_f32_32x32x16_bf16 v[50:65], v[88:91], v[70:73], v[50:65]
	s_waitcnt lgkmcnt(6)
	v_mfma_f32_32x32x16_bf16 v[50:65], v[92:95], v[74:77], v[50:65]
	s_waitcnt lgkmcnt(5)
	v_mfma_f32_32x32x16_bf16 v[50:65], v[96:99], v[78:81], v[50:65]
	s_waitcnt lgkmcnt(4)
	s_cmp_eq_u32 s7, 1
	s_cbranch_scc0 .Lat_c0s_11
	v_mfma_f32_32x32x16_bf16 v[34:49], v[100:103], v[66:69], 0
	s_branch .Lat_c0j_12
.Lat_c0s_11:
	v_mfma_f32_32x32x16_bf16 v[34:49], v[100:103], v[66:69], v[34:49]
.Lat_c0j_12:
	s_waitcnt lgkmcnt(3)
	v_mfma_f32_32x32x16_bf16 v[34:49], v[104:107], v[70:73], v[34:49]
	s_waitcnt lgkmcnt(2)
	v_mfma_f32_32x32x16_bf16 v[34:49], v[108:111], v[74:77], v[34:49]
	s_waitcnt lgkmcnt(1)
	v_mfma_f32_32x32x16_bf16 v[34:49], v[112:115], v[78:81], v[34:49]
	s_cmp_eq_u32 s5, 0
	s_cbranch_scc1 .Lat_nomask2_13
	s_nop 7
	s_nop 7
	v_cmp_le_i32_e32 vcc, 0, v120
	v_cmp_gt_i32_e64 s[8:9], 0, v121
	s_and_b64 vcc, s[8:9], vcc
	v_cndmask_b32_e32 v50, v242, v50, vcc
	v_cmp_le_i32_e32 vcc, 1, v120
	v_cmp_gt_i32_e64 s[8:9], 1, v121
	s_and_b64 vcc, s[8:9], vcc
	v_cndmask_b32_e32 v51, v242, v51, vcc
	v_cmp_le_i32_e32 vcc, 2, v120
	v_cmp_gt_i32_e64 s[8:9], 2, v121
	s_and_b64 vcc, s[8:9], vcc
	v_cndmask_b32_e32 v52, v242, v52, vcc
	v_cmp_le_i32_e32 vcc, 3, v120
	v_cmp_gt_i32_e64 s[8:9], 3, v121
	s_and_b64 vcc, s[8:9], vcc
	v_cndmask_b32_e32 v53, v242, v53, vcc
	v_cmp_le_i32_e32 vcc, 8, v120
	v_cmp_gt_i32_e64 s[8:9], 8, v121
	s_and_b64 vcc, s[8:9], vcc
	v_cndmask_b32_e32 v54, v242, v54, vcc
	v_cmp_le_i32_e32 vcc, 9, v120
	v_cmp_gt_i32_e64 s[8:9], 9, v121
	s_and_b64 vcc, s[8:9], vcc
	v_cndmask_b32_e32 v55, v242, v55, vcc
	v_cmp_le_i32_e32 vcc, 10, v120
	v_cmp_gt_i32_e64 s[8:9], 10, v121
	s_and_b64 vcc, s[8:9], vcc
	v_cndmask_b32_e32 v56, v242, v56, vcc
	v_cmp_le_i32_e32 vcc, 11, v120
	v_cmp_gt_i32_e64 s[8:9], 11, v121
	s_and_b64 vcc, s[8:9], vcc
	v_cndmask_b32_e32 v57, v242, v57, vcc
	v_cmp_le_i32_e32 vcc, 16, v120
	v_cmp_gt_i32_e64 s[8:9], 16, v121
	s_and_b64 vcc, s[8:9], vcc
	v_cndmask_b32_e32 v58, v242, v58, vcc
	v_cmp_le_i32_e32 vcc, 17, v120
	v_cmp_gt_i32_e64 s[8:9], 17, v121
	s_and_b64 vcc, s[8:9], vcc
	v_cndmask_b32_e32 v59, v242, v59, vcc
	v_cmp_le_i32_e32 vcc, 18, v120
	v_cmp_gt_i32_e64 s[8:9], 18, v121
	s_and_b64 vcc, s[8:9], vcc
	v_cndmask_b32_e32 v60, v242, v60, vcc
	v_cmp_le_i32_e32 vcc, 19, v120
	v_cmp_gt_i32_e64 s[8:9], 19, v121
; DI float fast_exp2(float x) { return __builtin_amdgcn_exp2f(x); }
; DI float half_max(float v) { auto rr = __builtin_amdgcn_permlane32_swap(__float_as_uint(v), __float_as_uint(v), false, false); return fmaxf(__uint_as_float(rr[0]), __uint_as_float(rr[1])); }
; DI float half_sum(float v) { auto rr = __builtin_amdgcn_permlane32_swap(__float_as_uint(v), __float_as_uint(v), false, false); return __uint_as_float(rr[0]) + __uint_as_float(rr[1]); }
; DI void attn_tile(LAS const unsigned char* Ks, LAS const unsigned char* VT, const bf16x8 (&qf)[4], int ql, int hi,
;                   bool need_mask, bool col_en, int lo_b, int hi_b, float& m_ref, float& l_run, f32x16 (&o)[2], f32x16 (&sp)[2]) {
;     ...
;             for (int r = 0; r < 16; ++r) { const int kvl = 32 * p + (r & 3) + 8 * (r >> 2) + 4 * hi; const bool ok = (kvl <= hi_b) && (kvl > lo_b); sp[p][r] = ok ? sp[p][r] : -INFINITY; }
;     }
;     float tm = fmaxf(fmaxf(sp[0][0], sp[0][1]), sp[1][0]);
; #pragma unroll
;     for (int r = 2; r < 16; r += 2) tm = fmaxf(fmaxf(tm, sp[0][r]), sp[0][r + 1]);
; #pragma unroll
;     for (int r = 1; r < 15; r += 2) tm = fmaxf(fmaxf(tm, sp[1][r]), sp[1][r + 1]);
;     tm = fmaxf(tm, sp[1][15]);
;     tm = half_max(tm);
;     if (__any((tm > 16.f) || ((tm < -16.f) && (tm > -INFINITY)))) {
;         const bool up = tm > 16.f;
;         const bool dn = (tm < -16.f) && (tm > -INFINITY) && (half_sum(l_run) == 0.f);
;         const float dlt = (up || dn) ? tm : 0.f;
;         const float alpha = up ? fast_exp2(-dlt) : 1.0f;
;         l_run *= alpha; m_ref += dlt;
; #pragma unroll
;         for (int r = 0; r < 16; ++r) { o[0][r] *= alpha; o[1][r] *= alpha; sp[0][r] -= dlt; sp[1][r] -= dlt; }
;     }
	s_and_b64 vcc, s[8:9], vcc
	v_cndmask_b32_e32 v61, v242, v61, vcc
	v_cmp_le_i32_e32 vcc, 24, v120
	v_cmp_gt_i32_e64 s[8:9], 24, v121
	s_and_b64 vcc, s[8:9], vcc
	v_cndmask_b32_e32 v62, v242, v62, vcc
	v_cmp_le_i32_e32 vcc, 25, v120
	v_cmp_gt_i32_e64 s[8:9], 25, v121
	s_and_b64 vcc, s[8:9], vcc
	v_cndmask_b32_e32 v63, v242, v63, vcc
	v_cmp_le_i32_e32 vcc, 26, v120
	v_cmp_gt_i32_e64 s[8:9], 26, v121
	s_and_b64 vcc, s[8:9], vcc
	v_cndmask_b32_e32 v64, v242, v64, vcc
	v_cmp_le_i32_e32 vcc, 27, v120
	v_cmp_gt_i32_e64 s[8:9], 27, v121
	s_and_b64 vcc, s[8:9], vcc
	v_cndmask_b32_e32 v65, v242, v65, vcc
	v_cmp_le_i32_e32 vcc, 32, v120
	v_cmp_gt_i32_e64 s[8:9], 32, v121
	s_and_b64 vcc, s[8:9], vcc
	v_cndmask_b32_e32 v34, v242, v34, vcc
	v_cmp_le_i32_e32 vcc, 33, v120
	v_cmp_gt_i32_e64 s[8:9], 33, v121
	s_and_b64 vcc, s[8:9], vcc
	v_cndmask_b32_e32 v35, v242, v35, vcc
	v_cmp_le_i32_e32 vcc, 34, v120
	v_cmp_gt_i32_e64 s[8:9], 34, v121
	s_and_b64 vcc, s[8:9], vcc
	v_cndmask_b32_e32 v36, v242, v36, vcc
	v_cmp_le_i32_e32 vcc, 35, v120
	v_cmp_gt_i32_e64 s[8:9], 35, v121
	s_and_b64 vcc, s[8:9], vcc
	v_cndmask_b32_e32 v37, v242, v37, vcc
	v_cmp_le_i32_e32 vcc, 40, v120
	v_cmp_gt_i32_e64 s[8:9], 40, v121
	s_and_b64 vcc, s[8:9], vcc
	v_cndmask_b32_e32 v38, v242, v38, vcc
	v_cmp_le_i32_e32 vcc, 41, v120
	v_cmp_gt_i32_e64 s[8:9], 41, v121
	s_and_b64 vcc, s[8:9], vcc
	v_cndmask_b32_e32 v39, v242, v39, vcc
	v_cmp_le_i32_e32 vcc, 42, v120
	v_cmp_gt_i32_e64 s[8:9], 42, v121
	s_and_b64 vcc, s[8:9], vcc
	v_cndmask_b32_e32 v40, v242, v40, vcc
	v_cmp_le_i32_e32 vcc, 43, v120
	v_cmp_gt_i32_e64 s[8:9], 43, v121
	s_and_b64 vcc, s[8:9], vcc
	v_cndmask_b32_e32 v41, v242, v41, vcc
	v_cmp_le_i32_e32 vcc, 48, v120
	v_cmp_gt_i32_e64 s[8:9], 48, v121
	s_and_b64 vcc, s[8:9], vcc
	v_cndmask_b32_e32 v42, v242, v42, vcc
	v_cmp_le_i32_e32 vcc, 49, v120
	v_cmp_gt_i32_e64 s[8:9], 49, v121
	s_and_b64 vcc, s[8:9], vcc
	v_cndmask_b32_e32 v43, v242, v43, vcc
	v_cmp_le_i32_e32 vcc, 50, v120
	v_cmp_gt_i32_e64 s[8:9], 50, v121
	s_and_b64 vcc, s[8:9], vcc
	v_cndmask_b32_e32 v44, v242, v44, vcc
	v_cmp_le_i32_e32 vcc, 51, v120
	v_cmp_gt_i32_e64 s[8:9], 51, v121
	s_and_b64 vcc, s[8:9], vcc
	v_cndmask_b32_e32 v45, v242, v45, vcc
	v_cmp_le_i32_e32 vcc, 56, v120
	v_cmp_gt_i32_e64 s[8:9], 56, v121
	s_and_b64 vcc, s[8:9], vcc
	v_cndmask_b32_e32 v46, v242, v46, vcc
	v_cmp_le_i32_e32 vcc, 57, v120
	v_cmp_gt_i32_e64 s[8:9], 57, v121
	s_and_b64 vcc, s[8:9], vcc
	v_cndmask_b32_e32 v47, v242, v47, vcc
	v_cmp_le_i32_e32 vcc, 58, v120
	v_cmp_gt_i32_e64 s[8:9], 58, v121
	s_and_b64 vcc, s[8:9], vcc
	v_cndmask_b32_e32 v48, v242, v48, vcc
	v_cmp_le_i32_e32 vcc, 59, v120
	v_cmp_gt_i32_e64 s[8:9], 59, v121
	s_and_b64 vcc, s[8:9], vcc
	v_cndmask_b32_e32 v49, v242, v49, vcc
.Lat_nomask2_13:
	v_max3_f32 v245, v50, v51, v52
	v_max3_f32 v245, v245, v53, v54
	v_max3_f32 v245, v245, v55, v56
	v_max3_f32 v245, v245, v57, v58
	v_max3_f32 v245, v245, v59, v60
	v_max3_f32 v245, v245, v61, v62
	v_max3_f32 v245, v245, v63, v64
	s_nop 3
	v_max3_f32 v245, v245, v65, v34
	v_max3_f32 v245, v245, v35, v36
	v_max3_f32 v245, v245, v37, v38
	v_max3_f32 v245, v245, v39, v40
	v_max3_f32 v245, v245, v41, v42
	v_max3_f32 v245, v245, v43, v44
	v_max3_f32 v245, v245, v45, v46
	v_max3_f32 v245, v245, v47, v48
	v_max_f32_e32 v245, v245, v49
	v_mov_b32_e32 v246, v245
	s_nop 1
	v_permlane32_swap_b32_e32 v245, v246
	v_max_f32_e32 v245, v245, v246
	s_cmp_eq_u32 s28, 1
	s_cbranch_scc1 .Lat_allen_14
	v_cndmask_b32_e64 v245, v242, v245, s[12:13]
.Lat_allen_14:
	v_cmp_gt_f32_e32 vcc, s66, v245
	v_cmp_lg_f32_e64 s[10:11], s64, v245
	v_cmp_lt_f32_e64 s[8:9], s65, v245
	s_and_b64 s[10:11], vcc, s[10:11]
	s_or_b64 vcc, s[8:9], s[10:11]
	s_cbranch_vccz .Lat_norescale_15
	v_mov_b32_e32 v130, v141
	v_mov_b32_e32 v129, v141
	s_nop 1
	v_permlane32_swap_b32_e32 v129, v130
	v_add_f32_e32 v129, v129, v130
	v_cmp_eq_f32_e32 vcc, 0, v129
	s_and_b64 s[10:11], s[10:11], vcc
	s_or_b64 vcc, s[8:9], s[10:11]
	v_cndmask_b32_e32 v128, 0, v245, vcc
	v_exp_f32_e64 v130, -v128
	v_add_f32_e32 v143, v143, v128
	v_cndmask_b32_e64 v117, 1.0, v130, s[8:9]
	v_mul_f32_e32 v141, v141, v117
	v_sub_f32_e32 v50, v50, v128
	v_sub_f32_e32 v51, v51, v128
	v_sub_f32_e32 v52, v52, v128
	v_sub_f32_e32 v53, v53, v128
	v_sub_f32_e32 v54, v54, v128
	v_sub_f32_e32 v55, v55, v128
	v_sub_f32_e32 v56, v56, v128
	v_sub_f32_e32 v57, v57, v128
	v_sub_f32_e32 v58, v58, v128
	v_sub_f32_e32 v59, v59, v128
	v_sub_f32_e32 v60, v60, v128
	v_sub_f32_e32 v61, v61, v128
	v_sub_f32_e32 v62, v62, v128
	v_sub_f32_e32 v63, v63, v128
	v_sub_f32_e32 v64, v64, v128
	v_sub_f32_e32 v65, v65, v128
	v_sub_f32_e32 v34, v34, v128
	v_sub_f32_e32 v35, v35, v128
	v_sub_f32_e32 v36, v36, v128
	v_sub_f32_e32 v37, v37, v128
	v_sub_f32_e32 v38, v38, v128
	v_sub_f32_e32 v39, v39, v128
	v_sub_f32_e32 v40, v40, v128
	v_sub_f32_e32 v41, v41, v128
	v_sub_f32_e32 v42, v42, v128
	v_sub_f32_e32 v43, v43, v128
	v_sub_f32_e32 v44, v44, v128
	v_sub_f32_e32 v45, v45, v128
	v_sub_f32_e32 v46, v46, v128
	v_sub_f32_e32 v47, v47, v128
	v_sub_f32_e32 v48, v48, v128
	v_sub_f32_e32 v49, v49, v128
	s_mov_b32 s68, 1
	v_mul_f32_e32 v18, v18, v117
	v_mul_f32_e32 v2, v2, v117
	v_mul_f32_e32 v19, v19, v117
	v_mul_f32_e32 v3, v3, v117
	v_mul_f32_e32 v20, v20, v117
	v_mul_f32_e32 v4, v4, v117
	v_mul_f32_e32 v21, v21, v117
	v_mul_f32_e32 v5, v5, v117
	v_mul_f32_e32 v22, v22, v117
	v_mul_f32_e32 v6, v6, v117
	v_mul_f32_e32 v23, v23, v117
	v_mul_f32_e32 v7, v7, v117
	v_mul_f32_e32 v24, v24, v117
	v_mul_f32_e32 v8, v8, v117
	v_mul_f32_e32 v25, v25, v117
	v_mul_f32_e32 v9, v9, v117
	v_mul_f32_e32 v26, v26, v117
	v_mul_f32_e32 v10, v10, v117
	v_mul_f32_e32 v27, v27, v117
	v_mul_f32_e32 v11, v11, v117
	v_mul_f32_e32 v28, v28, v117
	v_mul_f32_e32 v12, v12, v117
	v_mul_f32_e32 v29, v29, v117
	v_mul_f32_e32 v13, v13, v117
	v_mul_f32_e32 v30, v30, v117
	v_mul_f32_e32 v14, v14, v117
	v_mul_f32_e32 v31, v31, v117
	v_mul_f32_e32 v15, v15, v117
	v_mul_f32_e32 v32, v32, v117
	v_mul_f32_e32 v16, v16, v117
	v_mul_f32_e32 v33, v33, v117
	v_mul_f32_e32 v17, v17, v117
; DI unsigned pk2(float lo, float hi) { f32x2_t v = {lo, hi}; bf16x2_t b = __builtin_convertvector(v, bf16x2_t); return __builtin_bit_cast(unsigned, b); }
; DI float fast_exp2(float x) { return __builtin_amdgcn_exp2f(x); }
; #define DMA_TILE(Kp, Vp, slot) do { \
;         glds16((Kp) + kofs, (unsigned)__builtin_amdgcn_readfirstlane((int)(lds_base + (unsigned)((slot) * ATT_BUF + w * 1024)))); \
;         glds16((Vp) + vofs, (unsigned)__builtin_amdgcn_readfirstlane((int)(lds_base + (unsigned)((slot) * ATT_BUF + LDS_VT + w * 1024)))); } while (0)
; #define WAIT_VM(n) asm volatile("s_waitcnt vmcnt(" #n ")" ::: "memory")
; #define LBAR() do { asm volatile("s_waitcnt lgkmcnt(0)" ::: "memory"); __builtin_amdgcn_s_barrier(); asm volatile("" ::: "memory"); } while (0)
; #define TILE_SRC(ii, kp, vp) do { const int jn_ = LIST[(ii)]; const bool ns_ = (ii) < nsel; kp = KS + (ns_ ? (size_t)0 : 2 * KV_SLOT) + (size_t)jn_ * 4096; vp = kp + KV_SLOT; } while (0)
; DI void attn_tile(LAS const unsigned char* Ks, LAS const unsigned char* VT, const bf16x8 (&qf)[4], int ql, int hi,
;                   bool need_mask, bool col_en, int lo_b, int hi_b, float& m_ref, float& l_run, f32x16 (&o)[2], f32x16 (&sp)[2]) {
;     ...
;     f32x2_t ps = {0.f, 0.f};
; #pragma unroll
;     for (int r = 0; r < 16; ++r) { const float e0 = fast_exp2(sp[0][r]), e1 = fast_exp2(sp[1][r]); sp[0][r] = e0; sp[1][r] = e1; ps += (f32x2_t){e0, e1}; }
;     l_run += ps[0] + ps[1];
;     bf16x8 pk[2][2];
; #pragma unroll
;     for (int p = 0; p < 2; ++p)
; #pragma unroll
;         for (int s = 0; s < 2; ++s) { u32x4 w; w.x = pk2(sp[p][8 * s], sp[p][8 * s + 1]); w.y = pk2(sp[p][8 * s + 2], sp[p][8 * s + 3]); w.z = pk2(sp[p][8 * s + 4], sp[p][8 * s + 5]); w.w = pk2(sp[p][8 * s + 6], sp[p][8 * s + 7]); pk[p][s] = __builtin_bit_cast(bf16x8, w); }
; DI void attn_unit(LAS unsigned char* lds, const Args& a, int bg, int qt) {
;     ...
;     for (int i = 0; i < ntile; ++i) {
;         const int j = LIST[i]; const bool is_sel = i < nsel;
;         if (i + 2 < ntile) WAIT_VM(4); else if (i + 1 < ntile) WAIT_VM(2); else WAIT_VM(0);
;         LBAR();
;         if (i + 3 < ntile) { const bf16_t* kp; const bf16_t* vp; TILE_SRC(i + 3, kp, vp); DMA_TILE(kp, vp, (i + 1) & 3); }
.Lat_norescale_15:
	v_exp_f32_e32 v50, v50
	v_exp_f32_e32 v51, v51
	v_exp_f32_e32 v52, v52
	v_exp_f32_e32 v53, v53
	v_exp_f32_e32 v54, v54
	v_exp_f32_e32 v55, v55
	v_exp_f32_e32 v56, v56
	v_exp_f32_e32 v57, v57
	v_exp_f32_e32 v58, v58
	v_exp_f32_e32 v59, v59
	v_exp_f32_e32 v60, v60
	v_exp_f32_e32 v61, v61
	v_exp_f32_e32 v62, v62
	v_exp_f32_e32 v63, v63
	v_exp_f32_e32 v64, v64
	v_exp_f32_e32 v65, v65
	v_exp_f32_e32 v34, v34
	v_exp_f32_e32 v35, v35
	v_exp_f32_e32 v36, v36
	v_exp_f32_e32 v37, v37
	v_exp_f32_e32 v38, v38
	v_exp_f32_e32 v39, v39
	v_exp_f32_e32 v40, v40
	v_exp_f32_e32 v41, v41
	v_exp_f32_e32 v42, v42
	v_exp_f32_e32 v43, v43
	v_exp_f32_e32 v44, v44
	v_exp_f32_e32 v45, v45
	v_exp_f32_e32 v46, v46
	v_exp_f32_e32 v47, v47
	v_exp_f32_e32 v48, v48
	v_exp_f32_e32 v49, v49
	s_waitcnt lgkmcnt(0)
	v_readfirstlane_b32 s98, v254
	v_readfirstlane_b32 s99, v255
	s_mov_b64 s[16:17], s[12:13]
	s_mov_b32 s21, s28
	s_add_i32 s77, s77, 1
	s_cmp_lt_i32 s77, s100
.Lat_disp:
	s_cmp_eq_u32 s4, 0
	s_cbranch_scc1 .Lat_nodefer_16
	s_mov_b32 s4, 0
	s_nop 15
	v_mul_f32_e32 v18, v18, v117
	v_mul_f32_e32 v2, v2, v117
	v_mul_f32_e32 v19, v19, v117
	v_mul_f32_e32 v3, v3, v117
	v_mul_f32_e32 v20, v20, v117
	v_mul_f32_e32 v4, v4, v117
	v_mul_f32_e32 v21, v21, v117
	v_mul_f32_e32 v5, v5, v117
	v_mul_f32_e32 v22, v22, v117
	v_mul_f32_e32 v6, v6, v117
	v_mul_f32_e32 v23, v23, v117
	v_mul_f32_e32 v7, v7, v117
	v_mul_f32_e32 v24, v24, v117
	v_mul_f32_e32 v8, v8, v117
	v_mul_f32_e32 v25, v25, v117
	v_mul_f32_e32 v9, v9, v117
	v_mul_f32_e32 v26, v26, v117
	v_mul_f32_e32 v10, v10, v117
	v_mul_f32_e32 v27, v27, v117
	v_mul_f32_e32 v11, v11, v117
	v_mul_f32_e32 v28, v28, v117
	v_mul_f32_e32 v12, v12, v117
	v_mul_f32_e32 v29, v29, v117
	v_mul_f32_e32 v13, v13, v117
	v_mul_f32_e32 v30, v30, v117
	v_mul_f32_e32 v14, v14, v117
	v_mul_f32_e32 v31, v31, v117
	v_mul_f32_e32 v15, v15, v117
	v_mul_f32_e32 v32, v32, v117
	v_mul_f32_e32 v16, v16, v117
	v_mul_f32_e32 v33, v33, v117
	v_mul_f32_e32 v17, v17, v117
.Lat_nodefer_16:
	s_cmp_ge_i32 s77, s100
	s_cbranch_scc1 .Lat_drain
	s_cmp_eq_u32 s68, 0
	s_cbranch_scc0 .Lat_special
	s_cmp_le_i32 s77, s67
	s_cbranch_scc0 .Lat_special
	s_cmp_eq_u32 s101, 0
	s_cbranch_scc0 .Lat_hotentry_W
	s_add_i32 s8, s77, 2
	s_and_b32 s8, s8, 3
	s_lshl_b32 s8, s8, 14
	v_add_u32_e32 v134, s8, v240
	s_add_i32 s8, s77, 1
	s_and_b32 s8, s8, 3
	s_lshl_b32 s8, s8, 14
	v_add_u32_e32 v135, s8, v241
	s_and_b32 s63, s77, 3
	s_lshl_b32 s63, s63, 14
	s_add_i32 s63, s63, s75
	s_lshl2_add_u32 s8, s77, s70
	v_mov_b32_e32 v136, s8
	v_mov_b32_e32 v138, s98
	v_mov_b32_e32 v144, s99
	v_mov_b32_e32 v145, 0
	v_mov_b32_e32 v149, 0
.Lat_hot_S:
	s_waitcnt vmcnt(2) lgkmcnt(0)
	s_barrier
	ds_read_b128 v[84:87], v134
	ds_read_b128 v[88:91], v134 offset:2048
	ds_read_b128 v[92:95], v134 offset:4096
	ds_read_b128 v[96:99], v134 offset:6144
	ds_read_b128 v[100:103], v134 offset:512
	ds_read_b128 v[104:107], v134 offset:2560
	ds_read_b128 v[108:111], v134 offset:4608
	ds_read_b128 v[112:115], v134 offset:6656
	ds_read_b32 v140, v136 offset:4
	ds_read_b32 v142, v136 offset:12
	v_add_f32_e32 v118, v50, v51
	v_add_f32_e32 v119, v34, v35
	v_cvt_pk_bf16_f32 v224, v50, v51
	v_add_f32_e32 v118, v118, v52
	v_add_f32_e32 v119, v119, v36
	v_cvt_pk_bf16_f32 v225, v52, v53
	v_add_f32_e32 v118, v118, v53
	v_add_f32_e32 v119, v119, v37
	v_cvt_pk_bf16_f32 v226, v54, v55
	v_add_f32_e32 v118, v118, v54
	v_add_f32_e32 v119, v119, v38
	v_cvt_pk_bf16_f32 v227, v56, v57
	v_add_f32_e32 v118, v118, v55
	v_add_f32_e32 v119, v119, v39
	v_cvt_pk_bf16_f32 v228, v58, v59
	v_add_f32_e32 v118, v118, v56
	v_add_f32_e32 v119, v119, v40
	v_cvt_pk_bf16_f32 v229, v60, v61
	v_add_f32_e32 v118, v118, v57
	v_add_f32_e32 v119, v119, v41
	v_cvt_pk_bf16_f32 v230, v62, v63
	v_add_f32_e32 v118, v118, v58
	v_add_f32_e32 v119, v119, v42
	v_cvt_pk_bf16_f32 v231, v64, v65
	v_add_f32_e32 v118, v118, v59
	v_add_f32_e32 v119, v119, v43
	v_cvt_pk_bf16_f32 v232, v34, v35
	v_add_f32_e32 v118, v118, v60
	v_add_f32_e32 v119, v119, v44
	v_cvt_pk_bf16_f32 v233, v36, v37
	v_add_f32_e32 v118, v118, v61
	v_add_f32_e32 v119, v119, v45
	v_cvt_pk_bf16_f32 v234, v38, v39
	v_add_f32_e32 v118, v118, v62
	v_add_f32_e32 v119, v119, v46
	v_cvt_pk_bf16_f32 v235, v40, v41
	v_add_f32_e32 v118, v118, v63
	v_add_f32_e32 v119, v119, v47
	v_cvt_pk_bf16_f32 v236, v42, v43
	v_add_f32_e32 v118, v118, v64
	v_add_f32_e32 v119, v119, v48
	v_cvt_pk_bf16_f32 v237, v44, v45
	v_add_f32_e32 v118, v118, v65
	v_add_f32_e32 v119, v119, v49
	v_cvt_pk_bf16_f32 v238, v46, v47
	v_cvt_pk_bf16_f32 v239, v48, v49
	v_add_f32_e32 v118, v118, v119
	s_cmp_eq_u32 s69, 1
	s_cbranch_scc1 .Lat_hcep_17
	v_cndmask_b32_e64 v118, 0, v118, s[16:17]
	v_cndmask_b32_e64 v224, 0, v224, s[16:17]
	v_cndmask_b32_e64 v225, 0, v225, s[16:17]
	v_cndmask_b32_e64 v226, 0, v226, s[16:17]
	v_cndmask_b32_e64 v227, 0, v227, s[16:17]
	v_cndmask_b32_e64 v228, 0, v228, s[16:17]
	v_cndmask_b32_e64 v229, 0, v229, s[16:17]
	v_cndmask_b32_e64 v230, 0, v230, s[16:17]
	v_cndmask_b32_e64 v231, 0, v231, s[16:17]
	v_cndmask_b32_e64 v232, 0, v232, s[16:17]
	v_cndmask_b32_e64 v233, 0, v233, s[16:17]
	v_cndmask_b32_e64 v234, 0, v234, s[16:17]
	v_cndmask_b32_e64 v235, 0, v235, s[16:17]
	v_cndmask_b32_e64 v236, 0, v236, s[16:17]
	v_cndmask_b32_e64 v237, 0, v237, s[16:17]
	v_cndmask_b32_e64 v238, 0, v238, s[16:17]
	v_cndmask_b32_e64 v239, 0, v239, s[16:17]
; #define LAS __attribute__((address_space(3)))
; DI void attn_tile(LAS const unsigned char* Ks, LAS const unsigned char* VT, const bf16x8 (&qf)[4], int ql, int hi,
;                   bool need_mask, bool col_en, int lo_b, int hi_b, float& m_ref, float& l_run, f32x16 (&o)[2], f32x16 (&sp)[2]) {
;     ...
;     float tm = fmaxf(fmaxf(sp[0][0], sp[0][1]), sp[1][0]);
; #pragma unroll
;     for (int r = 2; r < 16; r += 2) tm = fmaxf(fmaxf(tm, sp[0][r]), sp[0][r + 1]);
; #pragma unroll
;     for (int r = 1; r < 15; r += 2) tm = fmaxf(fmaxf(tm, sp[1][r]), sp[1][r + 1]);
;     tm = fmaxf(tm, sp[1][15]);
;     tm = half_max(tm);
;     if (__any((tm > 16.f) || ((tm < -16.f) && (tm > -INFINITY)))) {
;         const bool up = tm > 16.f;
;         const bool dn = (tm < -16.f) && (tm > -INFINITY) && (half_sum(l_run) == 0.f);
;         const float dlt = (up || dn) ? tm : 0.f;
;         const float alpha = up ? fast_exp2(-dlt) : 1.0f;
;         l_run *= alpha; m_ref += dlt;
; #pragma unroll
;         for (int r = 0; r < 16; ++r) { o[0][r] *= alpha; o[1][r] *= alpha; sp[0][r] -= dlt; sp[1][r] -= dlt; }
;     }
;     f32x2_t ps = {0.f, 0.f};
; #pragma unroll
;     for (int r = 0; r < 16; ++r) { const float e0 = fast_exp2(sp[0][r]), e1 = fast_exp2(sp[1][r]); sp[0][r] = e0; sp[1][r] = e1; ps += (f32x2_t){e0, e1}; }
;     l_run += ps[0] + ps[1];
;     bf16x8 pk[2][2];
; #pragma unroll
;     for (int p = 0; p < 2; ++p)
; #pragma unroll
;         for (int s = 0; s < 2; ++s) { u32x4 w; w.x = pk2(sp[p][8 * s], sp[p][8 * s + 1]); w.y = pk2(sp[p][8 * s + 2], sp[p][8 * s + 3]); w.z = pk2(sp[p][8 * s + 4], sp[p][8 * s + 5]); w.w = pk2(sp[p][8 * s + 6], sp[p][8 * s + 7]); pk[p][s] = __builtin_bit_cast(bf16x8, w); }
;     LAS const unsigned char* vb = VT + ((lane_ >> 4) & 1) * 32 + (lane_ & 3) * 8 + (4 * hi + ((lane_ & 15) >> 2)) * 64;
; #pragma unroll
;     for (int dh = 0; dh < 2; ++dh) {
;         bf16x8 vf[4];
; #pragma unroll
;         for (int ks = 0; ks < 4; ++ks) {
;             const s16x4 lo = __builtin_bit_cast(s16x4, __builtin_amdgcn_ds_read_tr16_b64_v4i16((LAS v4i16_t*)(vb + dh * 4096 + ks * 1024)));
;             const s16x4 hh = __builtin_bit_cast(s16x4, __builtin_amdgcn_ds_read_tr16_b64_v4i16((LAS v4i16_t*)(vb + dh * 4096 + ks * 1024 + 512)));
;             vf[ks] = (bf16x8){lo[0], lo[1], lo[2], lo[3], hh[0], hh[1], hh[2], hh[3]};
;         }
; #pragma unroll
.Lat_hcep_17:
	v_add_f32_e32 v141, v141, v118
	v_bfe_u32 v247, v252, v138, 1
	v_lshlrev_b32_e32 v148, 13, v144
	s_mov_b32 m0, s63
	v_lshl_add_u64 v[122:123], v[186:187], 0, v[148:149]
	v_lshl_add_u64 v[124:125], v[188:189], 0, v[148:149]
	v_cmp_ne_u32_e64 s[12:13], 0, v247
	global_load_lds_dwordx4 v[122:123], off
	s_add_i32 m0, s63, 0x2000
	s_nop 0
	global_load_lds_dwordx4 v[124:125], off
	s_waitcnt lgkmcnt(0)
	v_mfma_f32_32x32x16_bf16 v[50:65], v[84:87], v[66:69], 0
	ds_read_b64_tr_b16 v[192:193], v135 offset:8192
	ds_read_b64_tr_b16 v[194:195], v135 offset:8704
	v_mfma_f32_32x32x16_bf16 v[50:65], v[88:91], v[70:73], v[50:65]
	ds_read_b64_tr_b16 v[208:209], v135 offset:12288
	ds_read_b64_tr_b16 v[210:211], v135 offset:12800
	v_mfma_f32_32x32x16_bf16 v[50:65], v[92:95], v[74:77], v[50:65]
	ds_read_b64_tr_b16 v[196:197], v135 offset:9216
	ds_read_b64_tr_b16 v[198:199], v135 offset:9728
	v_mfma_f32_32x32x16_bf16 v[50:65], v[96:99], v[78:81], v[50:65]
	ds_read_b64_tr_b16 v[212:213], v135 offset:13312
	ds_read_b64_tr_b16 v[214:215], v135 offset:13824
	v_mfma_f32_32x32x16_bf16 v[34:49], v[100:103], v[66:69], 0
	ds_read_b64_tr_b16 v[200:201], v135 offset:10240
	ds_read_b64_tr_b16 v[202:203], v135 offset:10752
	v_mfma_f32_32x32x16_bf16 v[34:49], v[104:107], v[70:73], v[34:49]
	ds_read_b64_tr_b16 v[216:217], v135 offset:14336
	ds_read_b64_tr_b16 v[218:219], v135 offset:14848
	v_mfma_f32_32x32x16_bf16 v[34:49], v[108:111], v[74:77], v[34:49]
	ds_read_b64_tr_b16 v[204:205], v135 offset:11264
	ds_read_b64_tr_b16 v[206:207], v135 offset:11776
	v_mfma_f32_32x32x16_bf16 v[34:49], v[112:115], v[78:81], v[34:49]
	ds_read_b64_tr_b16 v[220:221], v135 offset:15360
	ds_read_b64_tr_b16 v[222:223], v135 offset:15872
	s_waitcnt lgkmcnt(8)
	v_mfma_f32_32x32x16_bf16 v[18:33], v[192:195], v[224:227], v[18:33]
	v_mfma_f32_32x32x16_bf16 v[2:17], v[208:211], v[224:227], v[2:17]
	v_mfma_f32_32x32x16_bf16 v[18:33], v[196:199], v[228:231], v[18:33]
	v_mfma_f32_32x32x16_bf16 v[2:17], v[212:215], v[228:231], v[2:17]
	v_max3_f32 v245, v50, v51, v52
	v_max3_f32 v245, v245, v53, v54
	v_max3_f32 v245, v245, v55, v56
	v_max3_f32 v245, v245, v57, v58
	v_max3_f32 v245, v245, v59, v60
	v_max3_f32 v245, v245, v61, v62
	v_max3_f32 v245, v245, v63, v64
	v_max3_f32 v245, v245, v65, v34
	v_max3_f32 v245, v245, v35, v36
	v_max3_f32 v245, v245, v37, v38
	v_max3_f32 v245, v245, v39, v40
	v_max3_f32 v245, v245, v41, v42
	v_max3_f32 v245, v245, v43, v44
	v_max3_f32 v245, v245, v45, v46
	v_max3_f32 v245, v245, v47, v48
	v_max_f32_e32 v245, v245, v49
	v_mov_b32_e32 v246, v245
	s_nop 1
	v_permlane32_swap_b32_e32 v245, v246
	v_max_f32_e32 v245, v245, v246
	v_cndmask_b32_e64 v245, 0, v245, s[12:13]
	v_cmp_gt_f32_e64 vcc, |v245|, s65
	s_cmp_lg_u64 vcc, 0
	s_cbranch_scc1 .Lat_rare_S
.Lat_hotback_S:
	s_waitcnt lgkmcnt(0)
	v_mfma_f32_32x32x16_bf16 v[18:33], v[200:203], v[232:235], v[18:33]
	v_exp_f32_e32 v50, v50
	v_exp_f32_e32 v51, v51
	v_exp_f32_e32 v52, v52
	v_exp_f32_e32 v53, v53
	v_exp_f32_e32 v54, v54
	v_exp_f32_e32 v55, v55
	v_exp_f32_e32 v56, v56
	v_exp_f32_e32 v57, v57
	v_mfma_f32_32x32x16_bf16 v[2:17], v[216:219], v[232:235], v[2:17]
	v_exp_f32_e32 v58, v58
	v_exp_f32_e32 v59, v59
	v_exp_f32_e32 v60, v60
	v_exp_f32_e32 v61, v61
	v_exp_f32_e32 v62, v62
	v_exp_f32_e32 v63, v63
	v_exp_f32_e32 v64, v64
	v_exp_f32_e32 v65, v65
	v_mfma_f32_32x32x16_bf16 v[18:33], v[204:207], v[236:239], v[18:33]
	v_exp_f32_e32 v34, v34
	v_exp_f32_e32 v35, v35
	v_exp_f32_e32 v36, v36
	v_exp_f32_e32 v37, v37
	v_exp_f32_e32 v38, v38
	v_exp_f32_e32 v39, v39
	v_exp_f32_e32 v40, v40
	v_exp_f32_e32 v41, v41
	v_mfma_f32_32x32x16_bf16 v[2:17], v[220:223], v[236:239], v[2:17]
	v_exp_f32_e32 v42, v42
	v_exp_f32_e32 v43, v43
	v_exp_f32_e32 v44, v44
	v_exp_f32_e32 v45, v45
	v_exp_f32_e32 v46, v46
	v_exp_f32_e32 v47, v47
	v_exp_f32_e32 v48, v48
	v_exp_f32_e32 v49, v49
	v_add_u32_e32 v134, 0x4000, v134
	v_add_u32_e32 v135, 0x4000, v135
	s_add_i32 s63, s63, 0x4000
	v_and_b32_e32 v134, 0xffff, v134
	v_and_b32_e32 v135, 0xffff, v135
	s_and_b32 s63, s63, 0xffff
	v_add_u32_e32 v136, 4, v136
	v_mov_b32_e32 v138, v140
	v_mov_b32_e32 v144, v142
	s_mov_b64 s[16:17], s[12:13]
	s_add_i32 s77, s77, 1
	s_cmp_le_i32 s77, s67
	s_cbranch_scc1 .Lat_hot_S
	v_readfirstlane_b32 s98, v138
	v_readfirstlane_b32 s99, v144
	s_mov_b32 s21, s69
	s_branch .Lat_disp
.Lat_hotentry_W:
	s_add_i32 s8, s77, 2
	s_and_b32 s8, s8, 3
	s_lshl_b32 s8, s8, 14
	v_add_u32_e32 v134, s8, v240
	s_add_i32 s8, s77, 1
	s_and_b32 s8, s8, 3
	s_lshl_b32 s8, s8, 14
	v_add_u32_e32 v135, s8, v241
	s_and_b32 s63, s77, 3
	s_lshl_b32 s63, s63, 14
	s_add_i32 s63, s63, s75
	s_max_i32 s8, s20, 0
	s_add_i32 s8, s8, s77
	s_add_i32 s8, s8, 1
	s_sub_i32 s8, s8, s19
	s_lshl_b32 s8, s8, 13
	s_add_i32 s8, s8, 0x2000000
	s_add_u32 s8, s54, s8
	s_addc_u32 s9, s55, 0
	v_lshl_add_u64 v[190:191], s[8:9], 0, v[248:249]
	v_lshl_add_u64 v[82:83], s[8:9], 0, v[250:251]
	s_nop 0
	v_lshl_add_u64 v[82:83], v[82:83], 0, s[50:51]
; #define LAS __attribute__((address_space(3)))
; DI void attn_tile(LAS const unsigned char* Ks, LAS const unsigned char* VT, const bf16x8 (&qf)[4], int ql, int hi,
;                   bool need_mask, bool col_en, int lo_b, int hi_b, float& m_ref, float& l_run, f32x16 (&o)[2], f32x16 (&sp)[2]) {
;     ...
;         bf16x8 kf[4];
; #pragma unroll
;         for (int d0 = 0; d0 < 4; ++d0) { const int c = 2 * d0 + hi; kf[d0] = *(LAS const bf16x8*)(Ks + c * 1024 + ((ql + 32 * p) << 4)); }
;         f32x16 acc;
;         if (plain) {
; #pragma unroll
;             for (int r = 0; r < 16; ++r) acc[r] = 0.f;
; #pragma unroll
;             for (int d0 = 0; d0 < 4; ++d0) acc = MFMA32(kf[d0], qf[d0], acc);
;         } else {
; #pragma unroll
;             for (int r = 0; r < 16; ++r) acc[r] = bias;
; #pragma unroll
;             for (int d0 = 0; d0 < 4; ++d0) acc = MFMA32(kf[d0], qf[d0], acc);
;         }
;         sp[p] = acc;
;     }
;     if (need_mask) {
; #pragma unroll
;         for (int p = 0; p < 2; ++p)
; #pragma unroll
;             for (int r = 0; r < 16; ++r) { const int kvl = 32 * p + (r & 3) + 8 * (r >> 2) + 4 * hi; const bool ok = (kvl <= hi_b) && (kvl > lo_b); sp[p][r] = ok ? sp[p][r] : -INFINITY; }
;     }
;     float tm = fmaxf(fmaxf(sp[0][0], sp[0][1]), sp[1][0]);
; #pragma unroll
;     for (int r = 2; r < 16; r += 2) tm = fmaxf(fmaxf(tm, sp[0][r]), sp[0][r + 1]);
; #pragma unroll
;     for (int r = 1; r < 15; r += 2) tm = fmaxf(fmaxf(tm, sp[1][r]), sp[1][r + 1]);
;     tm = fmaxf(tm, sp[1][15]);
;     tm = half_max(tm);
;     if (__any((tm > 16.f) || ((tm < -16.f) && (tm > -INFINITY)))) {
;         const bool up = tm > 16.f;
;         const bool dn = (tm < -16.f) && (tm > -INFINITY) && (half_sum(l_run) == 0.f);
;         const float dlt = (up || dn) ? tm : 0.f;
;         const float alpha = up ? fast_exp2(-dlt) : 1.0f;
;         l_run *= alpha; m_ref += dlt;
; #pragma unroll
;         for (int r = 0; r < 16; ++r) { o[0][r] *= alpha; o[1][r] *= alpha; sp[0][r] -= dlt; sp[1][r] -= dlt; }
;     }
;     f32x2_t ps = {0.f, 0.f};
; #pragma unroll
;     for (int r = 0; r < 16; ++r) { const float e0 = fast_exp2(sp[0][r]), e1 = fast_exp2(sp[1][r]); sp[0][r] = e0; sp[1][r] = e1; ps += (f32x2_t){e0, e1}; }
;     l_run += ps[0] + ps[1];
;     bf16x8 pk[2][2];
; #pragma unroll
;     for (int p = 0; p < 2; ++p)
; #pragma unroll
.Lat_hot_W:
	s_waitcnt vmcnt(2) lgkmcnt(0)
	s_barrier
	ds_read_b128 v[84:87], v134
	ds_read_b128 v[88:91], v134 offset:2048
	ds_read_b128 v[92:95], v134 offset:4096
	ds_read_b128 v[96:99], v134 offset:6144
	ds_read_b128 v[100:103], v134 offset:512
	ds_read_b128 v[104:107], v134 offset:2560
	ds_read_b128 v[108:111], v134 offset:4608
	ds_read_b128 v[112:115], v134 offset:6656
	v_add_f32_e32 v118, v50, v51
	v_add_f32_e32 v119, v34, v35
	v_cvt_pk_bf16_f32 v224, v50, v51
	v_add_f32_e32 v118, v118, v52
	v_add_f32_e32 v119, v119, v36
	v_cvt_pk_bf16_f32 v225, v52, v53
	v_add_f32_e32 v118, v118, v53
	v_add_f32_e32 v119, v119, v37
	v_cvt_pk_bf16_f32 v226, v54, v55
	v_add_f32_e32 v118, v118, v54
	v_add_f32_e32 v119, v119, v38
	v_cvt_pk_bf16_f32 v227, v56, v57
	v_add_f32_e32 v118, v118, v55
	v_add_f32_e32 v119, v119, v39
	v_cvt_pk_bf16_f32 v228, v58, v59
	v_add_f32_e32 v118, v118, v56
	v_add_f32_e32 v119, v119, v40
	v_cvt_pk_bf16_f32 v229, v60, v61
	v_add_f32_e32 v118, v118, v57
	v_add_f32_e32 v119, v119, v41
	v_cvt_pk_bf16_f32 v230, v62, v63
	v_add_f32_e32 v118, v118, v58
	v_add_f32_e32 v119, v119, v42
	v_cvt_pk_bf16_f32 v231, v64, v65
	v_add_f32_e32 v118, v118, v59
	v_add_f32_e32 v119, v119, v43
	v_cvt_pk_bf16_f32 v232, v34, v35
	v_add_f32_e32 v118, v118, v60
	v_add_f32_e32 v119, v119, v44
	v_cvt_pk_bf16_f32 v233, v36, v37
	v_add_f32_e32 v118, v118, v61
	v_add_f32_e32 v119, v119, v45
	v_cvt_pk_bf16_f32 v234, v38, v39
	v_add_f32_e32 v118, v118, v62
	v_add_f32_e32 v119, v119, v46
	v_cvt_pk_bf16_f32 v235, v40, v41
	v_add_f32_e32 v118, v118, v63
	v_add_f32_e32 v119, v119, v47
	v_cvt_pk_bf16_f32 v236, v42, v43
	v_add_f32_e32 v118, v118, v64
	v_add_f32_e32 v119, v119, v48
	v_cvt_pk_bf16_f32 v237, v44, v45
	v_add_f32_e32 v118, v118, v65
	v_add_f32_e32 v119, v119, v49
	v_cvt_pk_bf16_f32 v238, v46, v47
	v_cvt_pk_bf16_f32 v239, v48, v49
	v_add_f32_e32 v118, v118, v119
	v_add_f32_e32 v141, v141, v118
	s_mov_b32 m0, s63
	v_lshl_add_u64 v[190:191], v[190:191], 0, s[46:47]
	v_lshl_add_u64 v[82:83], v[82:83], 0, s[46:47]
	global_load_lds_dwordx4 v[190:191], off
	s_add_i32 m0, s63, 0x2000
	s_nop 0
	global_load_lds_dwordx4 v[82:83], off
	s_waitcnt lgkmcnt(0)
	v_mfma_f32_32x32x16_bf16 v[50:65], v[84:87], v[66:69], 0
	ds_read_b64_tr_b16 v[192:193], v135 offset:8192
	ds_read_b64_tr_b16 v[194:195], v135 offset:8704
	v_mfma_f32_32x32x16_bf16 v[50:65], v[88:91], v[70:73], v[50:65]
	ds_read_b64_tr_b16 v[208:209], v135 offset:12288
	ds_read_b64_tr_b16 v[210:211], v135 offset:12800
	v_mfma_f32_32x32x16_bf16 v[50:65], v[92:95], v[74:77], v[50:65]
	ds_read_b64_tr_b16 v[196:197], v135 offset:9216
	ds_read_b64_tr_b16 v[198:199], v135 offset:9728
	v_mfma_f32_32x32x16_bf16 v[50:65], v[96:99], v[78:81], v[50:65]
	ds_read_b64_tr_b16 v[212:213], v135 offset:13312
	ds_read_b64_tr_b16 v[214:215], v135 offset:13824
	v_mfma_f32_32x32x16_bf16 v[34:49], v[100:103], v[66:69], 0
	ds_read_b64_tr_b16 v[200:201], v135 offset:10240
	ds_read_b64_tr_b16 v[202:203], v135 offset:10752
	v_mfma_f32_32x32x16_bf16 v[34:49], v[104:107], v[70:73], v[34:49]
	ds_read_b64_tr_b16 v[216:217], v135 offset:14336
	ds_read_b64_tr_b16 v[218:219], v135 offset:14848
	v_mfma_f32_32x32x16_bf16 v[34:49], v[108:111], v[74:77], v[34:49]
	ds_read_b64_tr_b16 v[204:205], v135 offset:11264
	ds_read_b64_tr_b16 v[206:207], v135 offset:11776
	v_mfma_f32_32x32x16_bf16 v[34:49], v[112:115], v[78:81], v[34:49]
	ds_read_b64_tr_b16 v[220:221], v135 offset:15360
	ds_read_b64_tr_b16 v[222:223], v135 offset:15872
	s_waitcnt lgkmcnt(8)
	v_mfma_f32_32x32x16_bf16 v[18:33], v[192:195], v[224:227], v[18:33]
	v_mfma_f32_32x32x16_bf16 v[2:17], v[208:211], v[224:227], v[2:17]
	v_mfma_f32_32x32x16_bf16 v[18:33], v[196:199], v[228:231], v[18:33]
	v_mfma_f32_32x32x16_bf16 v[2:17], v[212:215], v[228:231], v[2:17]
	v_max3_f32 v245, v50, v51, v52
	v_max3_f32 v245, v245, v53, v54
	v_max3_f32 v245, v245, v55, v56
	v_max3_f32 v245, v245, v57, v58
	v_max3_f32 v245, v245, v59, v60
	v_max3_f32 v245, v245, v61, v62
	v_max3_f32 v245, v245, v63, v64
	v_max3_f32 v245, v245, v65, v34
	v_max3_f32 v245, v245, v35, v36
	v_max3_f32 v245, v245, v37, v38
	v_max3_f32 v245, v245, v39, v40
	v_max3_f32 v245, v245, v41, v42
	v_max3_f32 v245, v245, v43, v44
	v_max3_f32 v245, v245, v45, v46
	v_max3_f32 v245, v245, v47, v48
	v_max_f32_e32 v245, v245, v49
	v_mov_b32_e32 v246, v245
	s_nop 1
	v_permlane32_swap_b32_e32 v245, v246
	v_max_f32_e32 v245, v245, v246
	v_cmp_gt_f32_e64 vcc, |v245|, s65
	s_cmp_lg_u64 vcc, 0
	s_cbranch_scc1 .Lat_rare_W
; #define LAS __attribute__((address_space(3)))
; DI unsigned pk2(float lo, float hi) { f32x2_t v = {lo, hi}; bf16x2_t b = __builtin_convertvector(v, bf16x2_t); return __builtin_bit_cast(unsigned, b); }
; DI float fast_exp2(float x) { return __builtin_amdgcn_exp2f(x); }
; DI void attn_tile(LAS const unsigned char* Ks, LAS const unsigned char* VT, const bf16x8 (&qf)[4], int ql, int hi,
;                   bool need_mask, bool col_en, int lo_b, int hi_b, float& m_ref, float& l_run, f32x16 (&o)[2], f32x16 (&sp)[2]) {
;     ...
;     if (__any((tm > 16.f) || ((tm < -16.f) && (tm > -INFINITY)))) {
;         const bool up = tm > 16.f;
;         const bool dn = (tm < -16.f) && (tm > -INFINITY) && (half_sum(l_run) == 0.f);
;         const float dlt = (up || dn) ? tm : 0.f;
;         const float alpha = up ? fast_exp2(-dlt) : 1.0f;
;         l_run *= alpha; m_ref += dlt;
; #pragma unroll
;         for (int r = 0; r < 16; ++r) { o[0][r] *= alpha; o[1][r] *= alpha; sp[0][r] -= dlt; sp[1][r] -= dlt; }
;     }
;     f32x2_t ps = {0.f, 0.f};
; #pragma unroll
;     for (int r = 0; r < 16; ++r) { const float e0 = fast_exp2(sp[0][r]), e1 = fast_exp2(sp[1][r]); sp[0][r] = e0; sp[1][r] = e1; ps += (f32x2_t){e0, e1}; }
;     l_run += ps[0] + ps[1];
;     bf16x8 pk[2][2];
; #pragma unroll
;     for (int p = 0; p < 2; ++p)
; #pragma unroll
;         for (int s = 0; s < 2; ++s) { u32x4 w; w.x = pk2(sp[p][8 * s], sp[p][8 * s + 1]); w.y = pk2(sp[p][8 * s + 2], sp[p][8 * s + 3]); w.z = pk2(sp[p][8 * s + 4], sp[p][8 * s + 5]); w.w = pk2(sp[p][8 * s + 6], sp[p][8 * s + 7]); pk[p][s] = __builtin_bit_cast(bf16x8, w); }
;     LAS const unsigned char* vb = VT + ((lane_ >> 4) & 1) * 32 + (lane_ & 3) * 8 + (4 * hi + ((lane_ & 15) >> 2)) * 64;
; #pragma unroll
;     for (int dh = 0; dh < 2; ++dh) {
;         bf16x8 vf[4];
; #pragma unroll
;         for (int ks = 0; ks < 4; ++ks) {
;             const s16x4 lo = __builtin_bit_cast(s16x4, __builtin_amdgcn_ds_read_tr16_b64_v4i16((LAS v4i16_t*)(vb + dh * 4096 + ks * 1024)));
;             const s16x4 hh = __builtin_bit_cast(s16x4, __builtin_amdgcn_ds_read_tr16_b64_v4i16((LAS v4i16_t*)(vb + dh * 4096 + ks * 1024 + 512)));
;             vf[ks] = (bf16x8){lo[0], lo[1], lo[2], lo[3], hh[0], hh[1], hh[2], hh[3]};
;         }
; #pragma unroll
;         for (int ks = 0; ks < 4; ++ks) o[dh] = MFMA32(vf[ks], pk[ks >> 1][ks & 1], o[dh]);
.Lat_hotback_W:
	s_waitcnt lgkmcnt(0)
	v_mfma_f32_32x32x16_bf16 v[18:33], v[200:203], v[232:235], v[18:33]
	v_exp_f32_e32 v50, v50
	v_exp_f32_e32 v51, v51
	v_exp_f32_e32 v52, v52
	v_exp_f32_e32 v53, v53
	v_exp_f32_e32 v54, v54
	v_exp_f32_e32 v55, v55
	v_exp_f32_e32 v56, v56
	v_exp_f32_e32 v57, v57
	v_mfma_f32_32x32x16_bf16 v[2:17], v[216:219], v[232:235], v[2:17]
	v_exp_f32_e32 v58, v58
	v_exp_f32_e32 v59, v59
	v_exp_f32_e32 v60, v60
	v_exp_f32_e32 v61, v61
	v_exp_f32_e32 v62, v62
	v_exp_f32_e32 v63, v63
	v_exp_f32_e32 v64, v64
	v_exp_f32_e32 v65, v65
	v_mfma_f32_32x32x16_bf16 v[18:33], v[204:207], v[236:239], v[18:33]
	v_exp_f32_e32 v34, v34
	v_exp_f32_e32 v35, v35
	v_exp_f32_e32 v36, v36
	v_exp_f32_e32 v37, v37
	v_exp_f32_e32 v38, v38
	v_exp_f32_e32 v39, v39
	v_exp_f32_e32 v40, v40
	v_exp_f32_e32 v41, v41
	v_mfma_f32_32x32x16_bf16 v[2:17], v[220:223], v[236:239], v[2:17]
	v_exp_f32_e32 v42, v42
	v_exp_f32_e32 v43, v43
	v_exp_f32_e32 v44, v44
	v_exp_f32_e32 v45, v45
	v_exp_f32_e32 v46, v46
	v_exp_f32_e32 v47, v47
	v_exp_f32_e32 v48, v48
	v_exp_f32_e32 v49, v49
	v_add_u32_e32 v134, 0x4000, v134
	v_add_u32_e32 v135, 0x4000, v135
	s_add_i32 s63, s63, 0x4000
	v_and_b32_e32 v134, 0xffff, v134
	v_and_b32_e32 v135, 0xffff, v135
	s_and_b32 s63, s63, 0xffff
	s_add_i32 s77, s77, 1
	s_cmp_le_i32 s77, s67
	s_cbranch_scc1 .Lat_hot_W
	s_mov_b32 s21, 1
	s_branch .Lat_disp
.Lat_rare_S:
	v_cmp_gt_f32_e32 vcc, s66, v245
	v_cmp_lg_f32_e64 s[10:11], s64, v245
	v_cmp_lt_f32_e64 s[8:9], s65, v245
	s_and_b64 s[10:11], vcc, s[10:11]
	v_mov_b32_e32 v130, v141
	v_mov_b32_e32 v129, v141
	s_nop 1
	v_permlane32_swap_b32_e32 v129, v130
	v_add_f32_e32 v129, v129, v130
	v_cmp_eq_f32_e32 vcc, 0, v129
	s_and_b64 s[10:11], s[10:11], vcc
	s_or_b64 vcc, s[8:9], s[10:11]
	v_cndmask_b32_e32 v128, 0, v245, vcc
	v_exp_f32_e64 v130, -v128
	v_add_f32_e32 v143, v143, v128
	v_cndmask_b32_e64 v117, 1.0, v130, s[8:9]
	v_mul_f32_e32 v141, v141, v117
	v_sub_f32_e32 v50, v50, v128
	v_sub_f32_e32 v51, v51, v128
	v_sub_f32_e32 v52, v52, v128
	v_sub_f32_e32 v53, v53, v128
	v_sub_f32_e32 v54, v54, v128
	v_sub_f32_e32 v55, v55, v128
	v_sub_f32_e32 v56, v56, v128
	v_sub_f32_e32 v57, v57, v128
	v_sub_f32_e32 v58, v58, v128
	v_sub_f32_e32 v59, v59, v128
	v_sub_f32_e32 v60, v60, v128
	v_sub_f32_e32 v61, v61, v128
	v_sub_f32_e32 v62, v62, v128
	v_sub_f32_e32 v63, v63, v128
	v_sub_f32_e32 v64, v64, v128
	v_sub_f32_e32 v65, v65, v128
	v_sub_f32_e32 v34, v34, v128
	v_sub_f32_e32 v35, v35, v128
	v_sub_f32_e32 v36, v36, v128
	v_sub_f32_e32 v37, v37, v128
	v_sub_f32_e32 v38, v38, v128
	v_sub_f32_e32 v39, v39, v128
	v_sub_f32_e32 v40, v40, v128
	v_sub_f32_e32 v41, v41, v128
	v_sub_f32_e32 v42, v42, v128
	v_sub_f32_e32 v43, v43, v128
	v_sub_f32_e32 v44, v44, v128
	v_sub_f32_e32 v45, v45, v128
	v_sub_f32_e32 v46, v46, v128
	v_sub_f32_e32 v47, v47, v128
	v_sub_f32_e32 v48, v48, v128
	v_sub_f32_e32 v49, v49, v128
	s_mov_b32 s4, 1
	s_mov_b32 s68, 1
	s_mov_b32 s67, s77
	s_branch .Lat_hotback_S

; #define DMA_TILE(Kp, Vp, slot) do { \
;         glds16((Kp) + kofs, (unsigned)__builtin_amdgcn_readfirstlane((int)(lds_base + (unsigned)((slot) * ATT_BUF + w * 1024)))); \
;         glds16((Vp) + vofs, (unsigned)__builtin_amdgcn_readfirstlane((int)(lds_base + (unsigned)((slot) * ATT_BUF + LDS_VT + w * 1024)))); } while (0)
; #define WAIT_VM(n) asm volatile("s_waitcnt vmcnt(" #n ")" ::: "memory")
; #define LBAR() do { asm volatile("s_waitcnt lgkmcnt(0)" ::: "memory"); __builtin_amdgcn_s_barrier(); asm volatile("" ::: "memory"); } while (0)
; #define TILE_SRC(ii, kp, vp) do { const int jn_ = LIST[(ii)]; const bool ns_ = (ii) < nsel; kp = KS + (ns_ ? (size_t)0 : 2 * KV_SLOT) + (size_t)jn_ * 4096; vp = kp + KV_SLOT; } while (0)
; DI void attn_unit(LAS unsigned char* lds, const Args& a, int bg, int qt) {
;     ...
;     for (int i = 0; i < ntile; ++i) {
;         const int j = LIST[i]; const bool is_sel = i < nsel;
;         if (i + 2 < ntile) WAIT_VM(4); else if (i + 1 < ntile) WAIT_VM(2); else WAIT_VM(0);
;         LBAR();
;         if (i + 3 < ntile) { const bf16_t* kp; const bf16_t* vp; TILE_SRC(i + 3, kp, vp); DMA_TILE(kp, vp, (i + 1) & 3); }
.Lat_special:
	s_add_i32 s8, s77, 1
	s_cmp_lt_i32 s8, s18
	s_cbranch_scc0 .Lat_w0_18

; DI unsigned pk2(float lo, float hi) { f32x2_t v = {lo, hi}; bf16x2_t b = __builtin_convertvector(v, bf16x2_t); return __builtin_bit_cast(unsigned, b); }
; DI float fast_exp2(float x) { return __builtin_amdgcn_exp2f(x); }
; DI void attn_tile(LAS const unsigned char* Ks, LAS const unsigned char* VT, const bf16x8 (&qf)[4], int ql, int hi,
;                   bool need_mask, bool col_en, int lo_b, int hi_b, float& m_ref, float& l_run, f32x16 (&o)[2], f32x16 (&sp)[2]) {
;     ...
;     f32x2_t ps = {0.f, 0.f};
; #pragma unroll
;     for (int r = 0; r < 16; ++r) { const float e0 = fast_exp2(sp[0][r]), e1 = fast_exp2(sp[1][r]); sp[0][r] = e0; sp[1][r] = e1; ps += (f32x2_t){e0, e1}; }
;     l_run += ps[0] + ps[1];
;     bf16x8 pk[2][2];
; #pragma unroll
;     for (int p = 0; p < 2; ++p)
; #pragma unroll
;         for (int s = 0; s < 2; ++s) { u32x4 w; w.x = pk2(sp[p][8 * s], sp[p][8 * s + 1]); w.y = pk2(sp[p][8 * s + 2], sp[p][8 * s + 3]); w.z = pk2(sp[p][8 * s + 4], sp[p][8 * s + 5]); w.w = pk2(sp[p][8 * s + 6], sp[p][8 * s + 7]); pk[p][s] = __builtin_bit_cast(bf16x8, w); }
; DI void attn_unit(LAS unsigned char* lds, const Args& a, int bg, int qt) {
;     ...
;         bool need_mask, col_en = true; int lo_b = -1, hi_b = 63;
;         if (is_sel) { need_mask = (j == qt); if (j == qt) hi_b = qloc; col_en = ((mask_q >> j) & 1u) != 0u; }
.Lat_nodma_21:
	v_add_u32_e32 v246, s79, v240
	v_mov_b32_e32 v116, s78
	ds_read_b128 v[84:87], v246
	ds_read_b128 v[88:91], v246 offset:2048
	ds_read_b128 v[92:95], v246 offset:4096
	ds_read_b128 v[96:99], v246 offset:6144
	ds_read_b128 v[100:103], v246 offset:512
	ds_read_b128 v[104:107], v246 offset:2560
	ds_read_b128 v[108:111], v246 offset:4608
	ds_read_b128 v[112:115], v246 offset:6656
	ds_read2_b32 v[254:255], v116 offset0:1 offset1:3
	s_add_i32 s9, s77, 1
	s_and_b32 s9, s9, 3
	s_lshl_b32 s9, s9, 14
	v_add_u32_e32 v126, s9, v241
	v_add_f32_e32 v118, v50, v51
	v_add_f32_e32 v119, v34, v35
	v_cvt_pk_bf16_f32 v224, v50, v51
	v_add_f32_e32 v118, v118, v52
	v_add_f32_e32 v119, v119, v36
	v_cvt_pk_bf16_f32 v225, v52, v53
	v_add_f32_e32 v118, v118, v53
	v_add_f32_e32 v119, v119, v37
	v_cvt_pk_bf16_f32 v226, v54, v55
	v_add_f32_e32 v118, v118, v54
	v_add_f32_e32 v119, v119, v38
	v_cvt_pk_bf16_f32 v227, v56, v57
	v_add_f32_e32 v118, v118, v55
	v_add_f32_e32 v119, v119, v39
	v_cvt_pk_bf16_f32 v228, v58, v59
	v_add_f32_e32 v118, v118, v56
	v_add_f32_e32 v119, v119, v40
	v_cvt_pk_bf16_f32 v229, v60, v61
	v_add_f32_e32 v118, v118, v57
	v_add_f32_e32 v119, v119, v41
	v_cvt_pk_bf16_f32 v230, v62, v63
	v_add_f32_e32 v118, v118, v58
	v_add_f32_e32 v119, v119, v42
	v_cvt_pk_bf16_f32 v231, v64, v65
	v_add_f32_e32 v118, v118, v59
	v_add_f32_e32 v119, v119, v43
	v_cvt_pk_bf16_f32 v232, v34, v35
	v_add_f32_e32 v118, v118, v60
	v_add_f32_e32 v119, v119, v44
	v_cvt_pk_bf16_f32 v233, v36, v37
	v_add_f32_e32 v118, v118, v61
	v_add_f32_e32 v119, v119, v45
	v_cvt_pk_bf16_f32 v234, v38, v39
	v_add_f32_e32 v118, v118, v62
	v_add_f32_e32 v119, v119, v46
	v_cvt_pk_bf16_f32 v235, v40, v41
	v_add_f32_e32 v118, v118, v63
	v_add_f32_e32 v119, v119, v47
	v_cvt_pk_bf16_f32 v236, v42, v43
	v_add_f32_e32 v118, v118, v64
	v_add_f32_e32 v119, v119, v48
	v_cvt_pk_bf16_f32 v237, v44, v45
	v_add_f32_e32 v118, v118, v65
	v_add_f32_e32 v119, v119, v49
	v_cvt_pk_bf16_f32 v238, v46, v47
	v_cvt_pk_bf16_f32 v239, v48, v49
	v_add_f32_e32 v118, v118, v119
	s_cmp_eq_u32 s21, 1
	s_cbranch_scc1 .Lat_cep_22
	v_cndmask_b32_e64 v118, 0, v118, s[16:17]
	v_cndmask_b32_e64 v224, 0, v224, s[16:17]
	v_cndmask_b32_e64 v225, 0, v225, s[16:17]
	v_cndmask_b32_e64 v226, 0, v226, s[16:17]
	v_cndmask_b32_e64 v227, 0, v227, s[16:17]
	v_cndmask_b32_e64 v228, 0, v228, s[16:17]
	v_cndmask_b32_e64 v229, 0, v229, s[16:17]
	v_cndmask_b32_e64 v230, 0, v230, s[16:17]
	v_cndmask_b32_e64 v231, 0, v231, s[16:17]
	v_cndmask_b32_e64 v232, 0, v232, s[16:17]
	v_cndmask_b32_e64 v233, 0, v233, s[16:17]
	v_cndmask_b32_e64 v234, 0, v234, s[16:17]
	v_cndmask_b32_e64 v235, 0, v235, s[16:17]
	v_cndmask_b32_e64 v236, 0, v236, s[16:17]
	v_cndmask_b32_e64 v237, 0, v237, s[16:17]
	v_cndmask_b32_e64 v238, 0, v238, s[16:17]
	v_cndmask_b32_e64 v239, 0, v239, s[16:17]
.Lat_cep_22:
	v_add_f32_e32 v141, v141, v118
	s_mov_b64 s[12:13], exec
	s_mov_b32 s28, 1
	s_cmp_lt_i32 s77, s19
	s_cselect_b32 s6, 1, 0
	s_cbranch_scc0 .Lat_nosel_23
	v_lshrrev_b32_e32 v247, s98, v252
	v_and_b32_e32 v247, 1, v247
	v_cmp_eq_u32_e64 s[12:13], 1, v247
	s_nop 3
	s_cmp_eq_u64 s[12:13], exec
	s_cselect_b32 s28, 1, 0

; #define LAS __attribute__((address_space(3)))
; #define MFMA32(a, b, c) __builtin_amdgcn_mfma_f32_32x32x16_bf16((a), (b), (c), 0, 0, 0)
; DI void attn_tile(LAS const unsigned char* Ks, LAS const unsigned char* VT, const bf16x8 (&qf)[4], int ql, int hi,
;                   bool need_mask, bool col_en, int lo_b, int hi_b, float& m_ref, float& l_run, f32x16 (&o)[2], f32x16 (&sp)[2]) {
;     ...
;         bf16x8 kf[4];
; #pragma unroll
;         for (int d0 = 0; d0 < 4; ++d0) { const int c = 2 * d0 + hi; kf[d0] = *(LAS const bf16x8*)(Ks + c * 1024 + ((ql + 32 * p) << 4)); }
;         f32x16 acc;
;         if (plain) {
; #pragma unroll
;             for (int r = 0; r < 16; ++r) acc[r] = 0.f;
; #pragma unroll
;             for (int d0 = 0; d0 < 4; ++d0) acc = MFMA32(kf[d0], qf[d0], acc);
;         } else {
; #pragma unroll
;             for (int r = 0; r < 16; ++r) acc[r] = bias;
; #pragma unroll
;             for (int d0 = 0; d0 < 4; ++d0) acc = MFMA32(kf[d0], qf[d0], acc);
;         }
;     ...
;     LAS const unsigned char* vb = VT + ((lane_ >> 4) & 1) * 32 + (lane_ & 3) * 8 + (4 * hi + ((lane_ & 15) >> 2)) * 64;
; #pragma unroll
;     for (int dh = 0; dh < 2; ++dh) {
;         bf16x8 vf[4];
; #pragma unroll
;         for (int ks = 0; ks < 4; ++ks) {
;             const s16x4 lo = __builtin_bit_cast(s16x4, __builtin_amdgcn_ds_read_tr16_b64_v4i16((LAS v4i16_t*)(vb + dh * 4096 + ks * 1024)));
;             const s16x4 hh = __builtin_bit_cast(s16x4, __builtin_amdgcn_ds_read_tr16_b64_v4i16((LAS v4i16_t*)(vb + dh * 4096 + ks * 1024 + 512)));
;             vf[ks] = (bf16x8){lo[0], lo[1], lo[2], lo[3], hh[0], hh[1], hh[2], hh[3]};
;         }
.Lat_c0j_28:
	ds_read_b64_tr_b16 v[192:193], v126 offset:8192
	ds_read_b64_tr_b16 v[194:195], v126 offset:8704
	s_waitcnt lgkmcnt(9)
	v_mfma_f32_32x32x16_bf16 v[50:65], v[88:91], v[70:73], v[50:65]
	ds_read_b64_tr_b16 v[208:209], v126 offset:12288
	ds_read_b64_tr_b16 v[210:211], v126 offset:12800
	s_waitcnt lgkmcnt(10)
	v_mfma_f32_32x32x16_bf16 v[50:65], v[92:95], v[74:77], v[50:65]
	ds_read_b64_tr_b16 v[196:197], v126 offset:9216
	ds_read_b64_tr_b16 v[198:199], v126 offset:9728
	s_waitcnt lgkmcnt(11)
	v_mfma_f32_32x32x16_bf16 v[50:65], v[96:99], v[78:81], v[50:65]
	ds_read_b64_tr_b16 v[212:213], v126 offset:13312
	ds_read_b64_tr_b16 v[214:215], v126 offset:13824
	s_waitcnt lgkmcnt(12)
	s_cmp_eq_u32 s7, 1
	s_cbranch_scc0 .Lat_c0s_29
	v_mfma_f32_32x32x16_bf16 v[34:49], v[100:103], v[66:69], 0
	s_branch .Lat_c0j_30

; #define LAS __attribute__((address_space(3)))
; #define MFMA32(a, b, c) __builtin_amdgcn_mfma_f32_32x32x16_bf16((a), (b), (c), 0, 0, 0)
; DI void attn_tile(LAS const unsigned char* Ks, LAS const unsigned char* VT, const bf16x8 (&qf)[4], int ql, int hi,
;                   bool need_mask, bool col_en, int lo_b, int hi_b, float& m_ref, float& l_run, f32x16 (&o)[2], f32x16 (&sp)[2]) {
;     ...
;     if (need_mask) {
; #pragma unroll
;         for (int p = 0; p < 2; ++p)
; #pragma unroll
;             for (int r = 0; r < 16; ++r) { const int kvl = 32 * p + (r & 3) + 8 * (r >> 2) + 4 * hi; const bool ok = (kvl <= hi_b) && (kvl > lo_b); sp[p][r] = ok ? sp[p][r] : -INFINITY; }
;     }
;     ...
;     LAS const unsigned char* vb = VT + ((lane_ >> 4) & 1) * 32 + (lane_ & 3) * 8 + (4 * hi + ((lane_ & 15) >> 2)) * 64;
; #pragma unroll
;     for (int dh = 0; dh < 2; ++dh) {
;         bf16x8 vf[4];
; #pragma unroll
;         for (int ks = 0; ks < 4; ++ks) {
;             const s16x4 lo = __builtin_bit_cast(s16x4, __builtin_amdgcn_ds_read_tr16_b64_v4i16((LAS v4i16_t*)(vb + dh * 4096 + ks * 1024)));
;             const s16x4 hh = __builtin_bit_cast(s16x4, __builtin_amdgcn_ds_read_tr16_b64_v4i16((LAS v4i16_t*)(vb + dh * 4096 + ks * 1024 + 512)));
;             vf[ks] = (bf16x8){lo[0], lo[1], lo[2], lo[3], hh[0], hh[1], hh[2], hh[3]};
;         }
; #pragma unroll
;         for (int ks = 0; ks < 4; ++ks) o[dh] = MFMA32(vf[ks], pk[ks >> 1][ks & 1], o[dh]);
.Lat_c0j_30:
	ds_read_b64_tr_b16 v[200:201], v126 offset:10240
	ds_read_b64_tr_b16 v[202:203], v126 offset:10752
	s_waitcnt lgkmcnt(13)
	v_mfma_f32_32x32x16_bf16 v[34:49], v[104:107], v[70:73], v[34:49]
	ds_read_b64_tr_b16 v[216:217], v126 offset:14336
	ds_read_b64_tr_b16 v[218:219], v126 offset:14848
	s_waitcnt lgkmcnt(14)
	v_mfma_f32_32x32x16_bf16 v[34:49], v[108:111], v[74:77], v[34:49]
	ds_read_b64_tr_b16 v[204:205], v126 offset:11264
	ds_read_b64_tr_b16 v[206:207], v126 offset:11776
	s_waitcnt lgkmcnt(15)
	v_mfma_f32_32x32x16_bf16 v[34:49], v[112:115], v[78:81], v[34:49]
	ds_read_b64_tr_b16 v[220:221], v126 offset:15360
	ds_read_b64_tr_b16 v[222:223], v126 offset:15872
	s_waitcnt lgkmcnt(14)
	v_mfma_f32_32x32x16_bf16 v[18:33], v[192:195], v[224:227], v[18:33]
	s_waitcnt lgkmcnt(12)
	v_mfma_f32_32x32x16_bf16 v[2:17], v[208:211], v[224:227], v[2:17]
	s_waitcnt lgkmcnt(10)
	v_mfma_f32_32x32x16_bf16 v[18:33], v[196:199], v[228:231], v[18:33]
	s_waitcnt lgkmcnt(8)
	v_mfma_f32_32x32x16_bf16 v[2:17], v[212:215], v[228:231], v[2:17]
	s_cmp_eq_u32 s5, 0
	s_cbranch_scc1 .Lat_nomask2_31
	s_nop 7
	s_nop 7
	v_cmp_le_i32_e32 vcc, 0, v120
	v_cmp_gt_i32_e64 s[8:9], 0, v121
	s_and_b64 vcc, s[8:9], vcc
	v_cndmask_b32_e32 v50, v242, v50, vcc
	v_cmp_le_i32_e32 vcc, 1, v120
	v_cmp_gt_i32_e64 s[8:9], 1, v121
	s_and_b64 vcc, s[8:9], vcc
	v_cndmask_b32_e32 v51, v242, v51, vcc
	v_cmp_le_i32_e32 vcc, 2, v120
	v_cmp_gt_i32_e64 s[8:9], 2, v121
	s_and_b64 vcc, s[8:9], vcc
	v_cndmask_b32_e32 v52, v242, v52, vcc
	v_cmp_le_i32_e32 vcc, 3, v120
	v_cmp_gt_i32_e64 s[8:9], 3, v121
	s_and_b64 vcc, s[8:9], vcc
	v_cndmask_b32_e32 v53, v242, v53, vcc
	v_cmp_le_i32_e32 vcc, 8, v120
	v_cmp_gt_i32_e64 s[8:9], 8, v121
	s_and_b64 vcc, s[8:9], vcc
	v_cndmask_b32_e32 v54, v242, v54, vcc
	v_cmp_le_i32_e32 vcc, 9, v120
	v_cmp_gt_i32_e64 s[8:9], 9, v121
	s_and_b64 vcc, s[8:9], vcc
	v_cndmask_b32_e32 v55, v242, v55, vcc
	v_cmp_le_i32_e32 vcc, 10, v120
	v_cmp_gt_i32_e64 s[8:9], 10, v121
	s_and_b64 vcc, s[8:9], vcc
	v_cndmask_b32_e32 v56, v242, v56, vcc
	v_cmp_le_i32_e32 vcc, 11, v120
	v_cmp_gt_i32_e64 s[8:9], 11, v121
	s_and_b64 vcc, s[8:9], vcc
	v_cndmask_b32_e32 v57, v242, v57, vcc
	v_cmp_le_i32_e32 vcc, 16, v120
	v_cmp_gt_i32_e64 s[8:9], 16, v121
	s_and_b64 vcc, s[8:9], vcc
	v_cndmask_b32_e32 v58, v242, v58, vcc
	v_cmp_le_i32_e32 vcc, 17, v120
	v_cmp_gt_i32_e64 s[8:9], 17, v121
	s_and_b64 vcc, s[8:9], vcc
	v_cndmask_b32_e32 v59, v242, v59, vcc
	v_cmp_le_i32_e32 vcc, 18, v120
	v_cmp_gt_i32_e64 s[8:9], 18, v121
	s_and_b64 vcc, s[8:9], vcc
	v_cndmask_b32_e32 v60, v242, v60, vcc
	v_cmp_le_i32_e32 vcc, 19, v120
	v_cmp_gt_i32_e64 s[8:9], 19, v121
	s_and_b64 vcc, s[8:9], vcc
	v_cndmask_b32_e32 v61, v242, v61, vcc
	v_cmp_le_i32_e32 vcc, 24, v120
	v_cmp_gt_i32_e64 s[8:9], 24, v121
	s_and_b64 vcc, s[8:9], vcc
	v_cndmask_b32_e32 v62, v242, v62, vcc
	v_cmp_le_i32_e32 vcc, 25, v120
	v_cmp_gt_i32_e64 s[8:9], 25, v121
	s_and_b64 vcc, s[8:9], vcc
	v_cndmask_b32_e32 v63, v242, v63, vcc
	v_cmp_le_i32_e32 vcc, 26, v120
	v_cmp_gt_i32_e64 s[8:9], 26, v121
	s_and_b64 vcc, s[8:9], vcc
	v_cndmask_b32_e32 v64, v242, v64, vcc
	v_cmp_le_i32_e32 vcc, 27, v120
	v_cmp_gt_i32_e64 s[8:9], 27, v121
	s_and_b64 vcc, s[8:9], vcc
	v_cndmask_b32_e32 v65, v242, v65, vcc
	v_cmp_le_i32_e32 vcc, 32, v120
	v_cmp_gt_i32_e64 s[8:9], 32, v121
	s_and_b64 vcc, s[8:9], vcc
	v_cndmask_b32_e32 v34, v242, v34, vcc
	v_cmp_le_i32_e32 vcc, 33, v120
	v_cmp_gt_i32_e64 s[8:9], 33, v121
	s_and_b64 vcc, s[8:9], vcc
	v_cndmask_b32_e32 v35, v242, v35, vcc
	v_cmp_le_i32_e32 vcc, 34, v120
	v_cmp_gt_i32_e64 s[8:9], 34, v121
	s_and_b64 vcc, s[8:9], vcc
	v_cndmask_b32_e32 v36, v242, v36, vcc
	v_cmp_le_i32_e32 vcc, 35, v120
	v_cmp_gt_i32_e64 s[8:9], 35, v121
	s_and_b64 vcc, s[8:9], vcc
	v_cndmask_b32_e32 v37, v242, v37, vcc
	v_cmp_le_i32_e32 vcc, 40, v120
	v_cmp_gt_i32_e64 s[8:9], 40, v121
	s_and_b64 vcc, s[8:9], vcc
	v_cndmask_b32_e32 v38, v242, v38, vcc
	v_cmp_le_i32_e32 vcc, 41, v120
	v_cmp_gt_i32_e64 s[8:9], 41, v121
	s_and_b64 vcc, s[8:9], vcc
	v_cndmask_b32_e32 v39, v242, v39, vcc
	v_cmp_le_i32_e32 vcc, 42, v120
	v_cmp_gt_i32_e64 s[8:9], 42, v121
	s_and_b64 vcc, s[8:9], vcc
	v_cndmask_b32_e32 v40, v242, v40, vcc
	v_cmp_le_i32_e32 vcc, 43, v120
	v_cmp_gt_i32_e64 s[8:9], 43, v121
	s_and_b64 vcc, s[8:9], vcc
	v_cndmask_b32_e32 v41, v242, v41, vcc
	v_cmp_le_i32_e32 vcc, 48, v120
	v_cmp_gt_i32_e64 s[8:9], 48, v121
	s_and_b64 vcc, s[8:9], vcc
	v_cndmask_b32_e32 v42, v242, v42, vcc
	v_cmp_le_i32_e32 vcc, 49, v120
	v_cmp_gt_i32_e64 s[8:9], 49, v121
	s_and_b64 vcc, s[8:9], vcc
	v_cndmask_b32_e32 v43, v242, v43, vcc
	v_cmp_le_i32_e32 vcc, 50, v120
	v_cmp_gt_i32_e64 s[8:9], 50, v121
	s_and_b64 vcc, s[8:9], vcc
	v_cndmask_b32_e32 v44, v242, v44, vcc
	v_cmp_le_i32_e32 vcc, 51, v120
	v_cmp_gt_i32_e64 s[8:9], 51, v121
	s_and_b64 vcc, s[8:9], vcc
	v_cndmask_b32_e32 v45, v242, v45, vcc
	v_cmp_le_i32_e32 vcc, 56, v120
	v_cmp_gt_i32_e64 s[8:9], 56, v121
	s_and_b64 vcc, s[8:9], vcc
	v_cndmask_b32_e32 v46, v242, v46, vcc
	v_cmp_le_i32_e32 vcc, 57, v120
	v_cmp_gt_i32_e64 s[8:9], 57, v121
	s_and_b64 vcc, s[8:9], vcc
	v_cndmask_b32_e32 v47, v242, v47, vcc
	v_cmp_le_i32_e32 vcc, 58, v120
	v_cmp_gt_i32_e64 s[8:9], 58, v121
	s_and_b64 vcc, s[8:9], vcc
	v_cndmask_b32_e32 v48, v242, v48, vcc
	v_cmp_le_i32_e32 vcc, 59, v120
	v_cmp_gt_i32_e64 s[8:9], 59, v121
	s_and_b64 vcc, s[8:9], vcc
	v_cndmask_b32_e32 v49, v242, v49, vcc

; #define LAS __attribute__((address_space(3)))
; DI unsigned pk2(float lo, float hi) { f32x2_t v = {lo, hi}; bf16x2_t b = __builtin_convertvector(v, bf16x2_t); return __builtin_bit_cast(unsigned, b); }
; DI float fast_exp2(float x) { return __builtin_amdgcn_exp2f(x); }
; DI void attn_tile(LAS const unsigned char* Ks, LAS const unsigned char* VT, const bf16x8 (&qf)[4], int ql, int hi,
;                   bool need_mask, bool col_en, int lo_b, int hi_b, float& m_ref, float& l_run, f32x16 (&o)[2], f32x16 (&sp)[2]) {
;     ...
;     if (__any((tm > 16.f) || ((tm < -16.f) && (tm > -INFINITY)))) {
;         const bool up = tm > 16.f;
;         const bool dn = (tm < -16.f) && (tm > -INFINITY) && (half_sum(l_run) == 0.f);
;         const float dlt = (up || dn) ? tm : 0.f;
;         const float alpha = up ? fast_exp2(-dlt) : 1.0f;
;         l_run *= alpha; m_ref += dlt;
; #pragma unroll
;         for (int r = 0; r < 16; ++r) { o[0][r] *= alpha; o[1][r] *= alpha; sp[0][r] -= dlt; sp[1][r] -= dlt; }
;     }
;     f32x2_t ps = {0.f, 0.f};
; #pragma unroll
;     for (int r = 0; r < 16; ++r) { const float e0 = fast_exp2(sp[0][r]), e1 = fast_exp2(sp[1][r]); sp[0][r] = e0; sp[1][r] = e1; ps += (f32x2_t){e0, e1}; }
;     l_run += ps[0] + ps[1];
;     bf16x8 pk[2][2];
; #pragma unroll
;     for (int p = 0; p < 2; ++p)
; #pragma unroll
;         for (int s = 0; s < 2; ++s) { u32x4 w; w.x = pk2(sp[p][8 * s], sp[p][8 * s + 1]); w.y = pk2(sp[p][8 * s + 2], sp[p][8 * s + 3]); w.z = pk2(sp[p][8 * s + 4], sp[p][8 * s + 5]); w.w = pk2(sp[p][8 * s + 6], sp[p][8 * s + 7]); pk[p][s] = __builtin_bit_cast(bf16x8, w); }
;     LAS const unsigned char* vb = VT + ((lane_ >> 4) & 1) * 32 + (lane_ & 3) * 8 + (4 * hi + ((lane_ & 15) >> 2)) * 64;
; #pragma unroll
;     for (int dh = 0; dh < 2; ++dh) {
;         bf16x8 vf[4];
; #pragma unroll
;         for (int ks = 0; ks < 4; ++ks) {
;             const s16x4 lo = __builtin_bit_cast(s16x4, __builtin_amdgcn_ds_read_tr16_b64_v4i16((LAS v4i16_t*)(vb + dh * 4096 + ks * 1024)));
;             const s16x4 hh = __builtin_bit_cast(s16x4, __builtin_amdgcn_ds_read_tr16_b64_v4i16((LAS v4i16_t*)(vb + dh * 4096 + ks * 1024 + 512)));
;             vf[ks] = (bf16x8){lo[0], lo[1], lo[2], lo[3], hh[0], hh[1], hh[2], hh[3]};
;         }
; #pragma unroll
;         for (int ks = 0; ks < 4; ++ks) o[dh] = MFMA32(vf[ks], pk[ks >> 1][ks & 1], o[dh]);
.Lat_allen_32:
	v_cmp_gt_f32_e32 vcc, s66, v245
	v_cmp_lg_f32_e64 s[10:11], s64, v245
	v_cmp_lt_f32_e64 s[8:9], s65, v245
	s_and_b64 s[10:11], vcc, s[10:11]
	s_or_b64 vcc, s[8:9], s[10:11]
	s_cbranch_vccz .Lat_norescale_33
	v_mov_b32_e32 v130, v141
	v_mov_b32_e32 v129, v141
	s_nop 1
	v_permlane32_swap_b32_e32 v129, v130
	v_add_f32_e32 v129, v129, v130
	v_cmp_eq_f32_e32 vcc, 0, v129
	s_and_b64 s[10:11], s[10:11], vcc
	s_or_b64 vcc, s[8:9], s[10:11]
	v_cndmask_b32_e32 v128, 0, v245, vcc
	v_exp_f32_e64 v130, -v128
	v_add_f32_e32 v143, v143, v128
	v_cndmask_b32_e64 v117, 1.0, v130, s[8:9]
	v_mul_f32_e32 v141, v141, v117
	v_sub_f32_e32 v50, v50, v128
	v_sub_f32_e32 v51, v51, v128
	v_sub_f32_e32 v52, v52, v128
	v_sub_f32_e32 v53, v53, v128
	v_sub_f32_e32 v54, v54, v128
	v_sub_f32_e32 v55, v55, v128
	v_sub_f32_e32 v56, v56, v128
	v_sub_f32_e32 v57, v57, v128
	v_sub_f32_e32 v58, v58, v128
	v_sub_f32_e32 v59, v59, v128
	v_sub_f32_e32 v60, v60, v128
	v_sub_f32_e32 v61, v61, v128
	v_sub_f32_e32 v62, v62, v128
	v_sub_f32_e32 v63, v63, v128
	v_sub_f32_e32 v64, v64, v128
	v_sub_f32_e32 v65, v65, v128
	v_sub_f32_e32 v34, v34, v128
	v_sub_f32_e32 v35, v35, v128
	v_sub_f32_e32 v36, v36, v128
	v_sub_f32_e32 v37, v37, v128
	v_sub_f32_e32 v38, v38, v128
	v_sub_f32_e32 v39, v39, v128
	v_sub_f32_e32 v40, v40, v128
	v_sub_f32_e32 v41, v41, v128
	v_sub_f32_e32 v42, v42, v128
	v_sub_f32_e32 v43, v43, v128
	v_sub_f32_e32 v44, v44, v128
	v_sub_f32_e32 v45, v45, v128
	v_sub_f32_e32 v46, v46, v128
	v_sub_f32_e32 v47, v47, v128
	v_sub_f32_e32 v48, v48, v128
	v_sub_f32_e32 v49, v49, v128
	s_mov_b32 s68, 1
	s_mov_b32 s4, 1
.Lat_norescale_33:
	s_waitcnt lgkmcnt(6)
	v_mfma_f32_32x32x16_bf16 v[18:33], v[200:203], v[232:235], v[18:33]
	v_exp_f32_e32 v50, v50
	v_exp_f32_e32 v51, v51
	v_exp_f32_e32 v52, v52
	v_exp_f32_e32 v53, v53
	v_exp_f32_e32 v54, v54
	v_exp_f32_e32 v55, v55
	v_exp_f32_e32 v56, v56
	v_exp_f32_e32 v57, v57
	s_waitcnt lgkmcnt(4)
	v_mfma_f32_32x32x16_bf16 v[2:17], v[216:219], v[232:235], v[2:17]
	v_exp_f32_e32 v58, v58
	v_exp_f32_e32 v59, v59
	v_exp_f32_e32 v60, v60
	v_exp_f32_e32 v61, v61
	v_exp_f32_e32 v62, v62
	v_exp_f32_e32 v63, v63
	v_exp_f32_e32 v64, v64
	v_exp_f32_e32 v65, v65
	s_waitcnt lgkmcnt(2)
	v_mfma_f32_32x32x16_bf16 v[18:33], v[204:207], v[236:239], v[18:33]
	v_exp_f32_e32 v34, v34
	v_exp_f32_e32 v35, v35
	v_exp_f32_e32 v36, v36
	v_exp_f32_e32 v37, v37
	v_exp_f32_e32 v38, v38
	v_exp_f32_e32 v39, v39
	v_exp_f32_e32 v40, v40
	v_exp_f32_e32 v41, v41
	s_waitcnt lgkmcnt(0)
	v_mfma_f32_32x32x16_bf16 v[2:17], v[220:223], v[236:239], v[2:17]
	v_exp_f32_e32 v42, v42
	v_exp_f32_e32 v43, v43
	v_exp_f32_e32 v44, v44
	v_exp_f32_e32 v45, v45
	v_exp_f32_e32 v46, v46
	v_exp_f32_e32 v47, v47
	v_exp_f32_e32 v48, v48
	v_exp_f32_e32 v49, v49
	s_waitcnt lgkmcnt(0)
	v_readfirstlane_b32 s98, v254
	v_readfirstlane_b32 s99, v255
	s_mov_b64 s[16:17], s[12:13]
	s_mov_b32 s21, s28
	s_add_i32 s77, s77, 1
	s_cmp_lt_i32 s77, s100
	s_branch .Lat_disp
.Lat_drain:
	s_add_i32 s9, s77, 1
	s_and_b32 s9, s9, 3
	s_lshl_b32 s9, s9, 14
	v_add_u32_e32 v126, s9, v241
	ds_read_b64_tr_b16 v[192:193], v126 offset:8192
	ds_read_b64_tr_b16 v[194:195], v126 offset:8704
	ds_read_b64_tr_b16 v[208:209], v126 offset:12288
	ds_read_b64_tr_b16 v[210:211], v126 offset:12800
	ds_read_b64_tr_b16 v[196:197], v126 offset:9216
	ds_read_b64_tr_b16 v[198:199], v126 offset:9728
	ds_read_b64_tr_b16 v[212:213], v126 offset:13312
	ds_read_b64_tr_b16 v[214:215], v126 offset:13824
	ds_read_b64_tr_b16 v[200:201], v126 offset:10240
	ds_read_b64_tr_b16 v[202:203], v126 offset:10752
	ds_read_b64_tr_b16 v[216:217], v126 offset:14336
	ds_read_b64_tr_b16 v[218:219], v126 offset:14848
	ds_read_b64_tr_b16 v[204:205], v126 offset:11264
	ds_read_b64_tr_b16 v[206:207], v126 offset:11776
	ds_read_b64_tr_b16 v[220:221], v126 offset:15360
	ds_read_b64_tr_b16 v[222:223], v126 offset:15872
	v_add_f32_e32 v118, v50, v51
	v_add_f32_e32 v119, v34, v35
	v_cvt_pk_bf16_f32 v224, v50, v51
	v_add_f32_e32 v118, v118, v52
	v_add_f32_e32 v119, v119, v36
	v_cvt_pk_bf16_f32 v225, v52, v53
	v_add_f32_e32 v118, v118, v53
	v_add_f32_e32 v119, v119, v37
	v_cvt_pk_bf16_f32 v226, v54, v55
	v_add_f32_e32 v118, v118, v54
	v_add_f32_e32 v119, v119, v38
	v_cvt_pk_bf16_f32 v227, v56, v57
	v_add_f32_e32 v118, v118, v55
	v_add_f32_e32 v119, v119, v39
	v_cvt_pk_bf16_f32 v228, v58, v59
	v_add_f32_e32 v118, v118, v56
	v_add_f32_e32 v119, v119, v40
	v_cvt_pk_bf16_f32 v229, v60, v61
	v_add_f32_e32 v118, v118, v57
	v_add_f32_e32 v119, v119, v41
	v_cvt_pk_bf16_f32 v230, v62, v63
	v_add_f32_e32 v118, v118, v58
	v_add_f32_e32 v119, v119, v42
	v_cvt_pk_bf16_f32 v231, v64, v65
	v_add_f32_e32 v118, v118, v59
	v_add_f32_e32 v119, v119, v43
	v_cvt_pk_bf16_f32 v232, v34, v35
	v_add_f32_e32 v118, v118, v60
	v_add_f32_e32 v119, v119, v44
	v_cvt_pk_bf16_f32 v233, v36, v37
	v_add_f32_e32 v118, v118, v61
	v_add_f32_e32 v119, v119, v45
	v_cvt_pk_bf16_f32 v234, v38, v39
	v_add_f32_e32 v118, v118, v62
	v_add_f32_e32 v119, v119, v46
	v_cvt_pk_bf16_f32 v235, v40, v41
	v_add_f32_e32 v118, v118, v63
	v_add_f32_e32 v119, v119, v47
	v_cvt_pk_bf16_f32 v236, v42, v43
	v_add_f32_e32 v118, v118, v64
	v_add_f32_e32 v119, v119, v48
	v_cvt_pk_bf16_f32 v237, v44, v45
	v_add_f32_e32 v118, v118, v65
	v_add_f32_e32 v119, v119, v49
	v_cvt_pk_bf16_f32 v238, v46, v47
	v_cvt_pk_bf16_f32 v239, v48, v49
	v_add_f32_e32 v118, v118, v119
	s_cmp_eq_u32 s21, 1
	s_cbranch_scc1 .Lat_cep_34
	v_cndmask_b32_e64 v118, 0, v118, s[16:17]
	v_cndmask_b32_e64 v224, 0, v224, s[16:17]
	v_cndmask_b32_e64 v225, 0, v225, s[16:17]
	v_cndmask_b32_e64 v226, 0, v226, s[16:17]
	v_cndmask_b32_e64 v227, 0, v227, s[16:17]
	v_cndmask_b32_e64 v228, 0, v228, s[16:17]
	v_cndmask_b32_e64 v229, 0, v229, s[16:17]
	v_cndmask_b32_e64 v230, 0, v230, s[16:17]
	v_cndmask_b32_e64 v231, 0, v231, s[16:17]
	v_cndmask_b32_e64 v232, 0, v232, s[16:17]
	v_cndmask_b32_e64 v233, 0, v233, s[16:17]
	v_cndmask_b32_e64 v234, 0, v234, s[16:17]
	v_cndmask_b32_e64 v235, 0, v235, s[16:17]
	v_cndmask_b32_e64 v236, 0, v236, s[16:17]
	v_cndmask_b32_e64 v237, 0, v237, s[16:17]
	v_cndmask_b32_e64 v238, 0, v238, s[16:17]
	v_cndmask_b32_e64 v239, 0, v239, s[16:17]
; #define LAS __attribute__((address_space(3)))
; #define MFMA32(a, b, c) __builtin_amdgcn_mfma_f32_32x32x16_bf16((a), (b), (c), 0, 0, 0)
; DI float half_sum(float v) { auto rr = __builtin_amdgcn_permlane32_swap(__float_as_uint(v), __float_as_uint(v), false, false); return __uint_as_float(rr[0]) + __uint_as_float(rr[1]); }
; DI void attn_tile(LAS const unsigned char* Ks, LAS const unsigned char* VT, const bf16x8 (&qf)[4], int ql, int hi,
;                   bool need_mask, bool col_en, int lo_b, int hi_b, float& m_ref, float& l_run, f32x16 (&o)[2], f32x16 (&sp)[2]) {
;     ...
;     for (int dh = 0; dh < 2; ++dh) {
;         bf16x8 vf[4];
; #pragma unroll
;         for (int ks = 0; ks < 4; ++ks) {
;             const s16x4 lo = __builtin_bit_cast(s16x4, __builtin_amdgcn_ds_read_tr16_b64_v4i16((LAS v4i16_t*)(vb + dh * 4096 + ks * 1024)));
;             const s16x4 hh = __builtin_bit_cast(s16x4, __builtin_amdgcn_ds_read_tr16_b64_v4i16((LAS v4i16_t*)(vb + dh * 4096 + ks * 1024 + 512)));
;             vf[ks] = (bf16x8){lo[0], lo[1], lo[2], lo[3], hh[0], hh[1], hh[2], hh[3]};
;         }
; #pragma unroll
;         for (int ks = 0; ks < 4; ++ks) o[dh] = MFMA32(vf[ks], pk[ks >> 1][ks & 1], o[dh]);
; DI void attn_unit(LAS unsigned char* lds, const Args& a, int bg, int qt) {
;     ...
;         if (i == nsel) {
;             const float lt = half_sum(l_run); const float gi = GT[512] / lt;
; #pragma unroll
;             for (int r = 0; r < 16; ++r) { oacc[0][r] += gi * o[0][r]; oacc[1][r] += gi * o[1][r]; o[0][r] = 0.f; o[1][r] = 0.f; }
;             m_ref = 0.f; l_run = 0.f;
;         }
.Lat_cep_34:
	v_add_f32_e32 v141, v141, v118
	s_nop 1
	s_waitcnt lgkmcnt(14)
	v_mfma_f32_32x32x16_bf16 v[18:33], v[192:195], v[224:227], v[18:33]
	s_waitcnt lgkmcnt(12)
	v_mfma_f32_32x32x16_bf16 v[2:17], v[208:211], v[224:227], v[2:17]
	s_waitcnt lgkmcnt(10)
	v_mfma_f32_32x32x16_bf16 v[18:33], v[196:199], v[228:231], v[18:33]
	s_waitcnt lgkmcnt(8)
	v_mfma_f32_32x32x16_bf16 v[2:17], v[212:215], v[228:231], v[2:17]
	s_waitcnt lgkmcnt(6)
	v_mfma_f32_32x32x16_bf16 v[18:33], v[200:203], v[232:235], v[18:33]
	s_waitcnt lgkmcnt(4)
	v_mfma_f32_32x32x16_bf16 v[2:17], v[216:219], v[232:235], v[2:17]
	s_waitcnt lgkmcnt(2)
	v_mfma_f32_32x32x16_bf16 v[18:33], v[204:207], v[236:239], v[18:33]
	s_waitcnt lgkmcnt(0)
	v_mfma_f32_32x32x16_bf16 v[2:17], v[220:223], v[236:239], v[2:17]
	s_cmp_eq_u32 s101, 0
	s_cbranch_scc0 .Lat_exit
	ds_read_b32 v131, v133 offset:2048
	v_mov_b32_e32 v130, v141
	v_mov_b32_e32 v129, v141
	s_nop 1
	v_permlane32_swap_b32_e32 v129, v130
	v_add_f32_e32 v129, v129, v130
	s_waitcnt lgkmcnt(0)
	v_div_scale_f32 v130, s[8:9], v129, v129, v131
	v_rcp_f32_e32 v132, v130
	v_div_scale_f32 v82, vcc, v131, v129, v131
	v_fma_f32 v83, -v130, v132, 1.0
	v_fmac_f32_e32 v132, v83, v132
	v_mul_f32_e32 v83, v82, v132
	v_fma_f32 v128, -v130, v83, v82
	v_fmac_f32_e32 v83, v128, v132
	v_fma_f32 v130, -v130, v83, v82
	v_div_fmas_f32 v130, v130, v132, v83
	v_div_fixup_f32 v117, v130, v129, v131
	s_nop 7
	v_fmac_f32_e32 v166, v117, v2
	v_fmac_f32_e32 v167, v117, v3
	v_fmac_f32_e32 v164, v117, v4
	v_fmac_f32_e32 v165, v117, v5
	v_fmac_f32_e32 v162, v117, v6
	v_fmac_f32_e32 v163, v117, v7
	v_fmac_f32_e32 v160, v117, v8
	v_fmac_f32_e32 v161, v117, v9
	v_fmac_f32_e32 v158, v117, v10
	v_fmac_f32_e32 v159, v117, v11
	v_fmac_f32_e32 v156, v117, v12
	v_fmac_f32_e32 v157, v117, v13
	v_fmac_f32_e32 v154, v117, v14
	v_fmac_f32_e32 v155, v117, v15
	v_fmac_f32_e32 v152, v117, v16
	v_fmac_f32_e32 v153, v117, v17
	v_fmac_f32_e32 v182, v117, v18
	v_fmac_f32_e32 v183, v117, v19
	v_fmac_f32_e32 v180, v117, v20
	v_fmac_f32_e32 v181, v117, v21
	v_fmac_f32_e32 v178, v117, v22
	v_fmac_f32_e32 v179, v117, v23
	v_fmac_f32_e32 v176, v117, v24
	v_fmac_f32_e32 v177, v117, v25
	v_fmac_f32_e32 v174, v117, v26
	v_fmac_f32_e32 v175, v117, v27
	v_fmac_f32_e32 v172, v117, v28
	v_fmac_f32_e32 v173, v117, v29
	v_fmac_f32_e32 v170, v117, v30
	v_fmac_f32_e32 v171, v117, v31
	v_fmac_f32_e32 v168, v117, v32
	v_fmac_f32_e32 v169, v117, v33
	v_mov_b32_e32 v18, 0
	v_mov_b32_e32 v2, 0
	v_mov_b32_e32 v19, 0
	v_mov_b32_e32 v3, 0
	v_mov_b32_e32 v20, 0
	v_mov_b32_e32 v4, 0
	v_mov_b32_e32 v21, 0
	v_mov_b32_e32 v5, 0
	v_mov_b32_e32 v22, 0
	v_mov_b32_e32 v6, 0
	v_mov_b32_e32 v23, 0
	v_mov_b32_e32 v7, 0
	v_mov_b32_e32 v24, 0
	v_mov_b32_e32 v8, 0
	v_mov_b32_e32 v25, 0
	v_mov_b32_e32 v9, 0
	v_mov_b32_e32 v26, 0
	v_mov_b32_e32 v10, 0
	v_mov_b32_e32 v27, 0
	v_mov_b32_e32 v11, 0
	v_mov_b32_e32 v28, 0
	v_mov_b32_e32 v12, 0
	v_mov_b32_e32 v29, 0
	v_mov_b32_e32 v13, 0
	v_mov_b32_e32 v30, 0
	v_mov_b32_e32 v14, 0
	v_mov_b32_e32 v31, 0
	v_mov_b32_e32 v15, 0
	v_mov_b32_e32 v32, 0
	v_mov_b32_e32 v16, 0
	v_mov_b32_e32 v33, 0
	v_mov_b32_e32 v17, 0
	v_mov_b32_e32 v141, 0
	v_mov_b32_e32 v143, 0
	s_mov_b32 s101, 1
	s_mov_b32 s100, s18
	s_add_i32 s67, s18, -3
	s_mov_b32 s68, 0
	s_branch .Lat_first
; #define LAS __attribute__((address_space(3)))
; DI void attn_unit(LAS unsigned char* lds, const Args& a, int bg, int qt) {
;     const int tid = threadIdx.x, lane = tid & 63, w = __builtin_amdgcn_readfirstlane(tid >> 6);
;     const int hl = w >> 1, qs = w & 1, ql = lane & 31, hi = lane >> 5, qloc = 32 * qs + ql;
;     const int b = bg >> 1, g = bg & 1, head = g * 4 + hl;
;     const size_t tok = (size_t)b * SEQ + qt * 64 + qloc;
;     const bf16_t* Qb = (const bf16_t*)(a.ws + WS_Q); const bf16_t* KVb = (const bf16_t*)(a.ws + WS_KV);
;     const float* NG = (const float*)(a.ws + WS_NG); bf16_t* AO = (bf16_t*)(a.ws + WS_AO);
;     bf16x8 qf[4];
;     { const bf16_t* qp = Qb + tok * 512 + head * 64 + hi * 8;
; #pragma unroll
;       for (int d0 = 0; d0 < 4; ++d0) qf[d0] = *(const bf16x8*)(qp + 16 * d0); }
;     LAS float* GT = (LAS float*)(lds + LDS_GATE) + tid;
;     GT[0] = NG[tok * 24 + head]; GT[512] = NG[tok * 24 + 8 + head]; GT[1024] = NG[tok * 24 + 16 + head];
;     LAS float* IMP = (LAS float*)(lds + LDS_IMP); LAS float* VAL = (LAS float*)(lds + LDS_VAL);
;     LAS unsigned* MSK = (LAS unsigned*)(lds + LDS_MSK); LAS int* LIST = (LAS int*)(lds + LDS_LIST);
;     const unsigned lds_base = (unsigned)(uintptr_t)lds;
;     const size_t kofs = (size_t)lane * 64 + w * 8;
;     const size_t vofs = (size_t)(16 * (w & 3) + (lane >> 2)) * 64 + 32 * (w >> 2) + 8 * (lane & 3);
;     ...
;     const bf16_t* KC = (const bf16_t*)(a.ws + WS_KCC) + (size_t)bg * 8192;
;     const bf16_t* KS = KVb + 2 * KV_SLOT + (size_t)bg * SEQ * 64;
;     constexpr size_t VC_OFF = (WS_VCC - WS_KCC) / 2;
;     f32x16 oacc[2], o[2], sp[2];
; #pragma unroll
;     for (int r = 0; r < 16; ++r) { oacc[0][r] = 0.f; oacc[1][r] = 0.f; o[0][r] = 0.f; o[1][r] = 0.f; }
;     float m_ref = 0.f, l_run = 0.f;
;     const int pos = qt * 64 + qloc;
;     float mu0 = 0.f, xcross = 0.f;
;     LAS float* ip = IMP + (hl * 64 + qloc) * IMP_PITCH;
.Lat_exit:
	s_mov_b32 m0, s29
	s_nop 7
	s_nop 3
	v_lshlrev_b32_e32 v36, 1, v184
	v_and_b32_e32 v98, 31, v184
	v_lshrrev_b32_e32 v34, 5, v146
	v_lshlrev_b32_e32 v35, 3, v184
	s_add_i32 s4, 0, 0x1ac00
	v_and_b32_e32 v189, 32, v36
	v_lshlrev_b32_e32 v102, 3, v34
	v_lshl_add_u32 v133, v184, 2, s4
	v_and_b32_e32 v185, 24, v35
	s_add_i32 s4, 0, 0x10000
	v_lshlrev_b32_e32 v1, 2, v34
	v_lshlrev_b32_e32 v187, 10, v34
	v_lshlrev_b32_e32 v190, 8, v34
	v_add_u32_e32 v34, 0, v189
	v_lshlrev_b32_e32 v36, 2, v98
	s_add_i32 s10, 0, 0x18400
	v_add3_u32 v39, v34, v185, v190
	v_lshrrev_b32_e32 v34, 5, v184
	v_add_u32_e32 v41, s4, v36
	v_add_u32_e32 v36, s10, v36
	s_add_i32 s10, 0, 0x1c400
	v_mad_u32_u24 v192, v34, 12, s10
	v_lshrrev_b32_e32 v38, 2, v184
	v_and_b32_e32 v38, 4, v38
	v_add_u32_e32 v194, 0x300, v192
	v_add_u32_e32 v196, 0x600, v192
	v_add_u32_e32 v198, 0x900, v192
	v_add_u32_e32 v40, 16, v34
	v_add_u32_e32 v200, 0xc0, v192
	v_add_u32_e32 v202, 0x3c0, v192
	v_add_u32_e32 v204, 0x6c0, v192
	v_add_u32_e32 v206, 0x9c0, v192
	v_or_b32_e32 v45, 32, v34
	v_add_u32_e32 v208, 0x180, v192
	v_add_u32_e32 v210, 0x480, v192
	v_add_u32_e32 v212, 0x780, v192
	v_add_u32_e32 v214, 0xa80, v192
	v_add_u32_e32 v47, 48, v34
	v_add_u32_e32 v216, 0x240, v192
	v_add_u32_e32 v218, 0x540, v192
	v_add_u32_e32 v220, 0x840, v192
	v_add_u32_e32 v222, 0xb40, v192
	v_add_u32_e32 v193, v192, v38
	v_add_u32_e32 v195, v194, v38
	v_add_u32_e32 v197, v196, v38
	v_add_u32_e32 v199, v198, v38
	v_lshlrev_b32_e32 v44, 7, v34
	v_add_u32_e32 v201, v200, v38
	v_add_u32_e32 v203, v202, v38
	v_add_u32_e32 v205, v204, v38
	v_add_u32_e32 v207, v206, v38
	v_lshlrev_b32_e32 v42, 7, v40
	v_add_u32_e32 v209, v208, v38
	v_add_u32_e32 v211, v210, v38
	v_add_u32_e32 v213, v212, v38
	v_add_u32_e32 v215, v214, v38
	v_lshlrev_b32_e32 v46, 7, v45
	v_add_u32_e32 v217, v216, v38
	v_add_u32_e32 v219, v218, v38
	v_add_u32_e32 v221, v220, v38
	v_add_u32_e32 v223, v222, v38
	v_lshlrev_b32_e32 v38, 7, v47
	v_add_u32_e32 v224, v36, v44
	s_add_i32 s10, 0, 0x1a400
	v_add_u32_e32 v226, v36, v42
	v_add_u32_e32 v228, v36, v46
	v_add_u32_e32 v230, v36, v38
	v_lshrrev_b32_e32 v36, 3, v146
	v_lshlrev_b32_e32 v188, 4, v98
	v_mul_u32_u24_e32 v43, 0x84, v34
	v_lshl_add_u32 v225, v34, 2, s10
	v_and_b32_e32 v34, 56, v35
	v_mul_u32_u24_e32 v233, 0x90, v36
	v_lshlrev_b32_e32 v36, 9, v36
	v_and_b32_e32 v191, 0xc0, v188
	v_add_u32_e32 v37, 0, v187
	v_lshl_add_u32 v227, v40, 2, s10
	v_or_b32_e32 v38, 0x1000, v36
	v_or_b32_e32 v40, 0x2000, v36
	v_or_b32_e32 v42, 0x3000, v36
	v_lshlrev_b32_e32 v138, 1, v34
	v_mbcnt_lo_u32_b32 v34, -1, 0
	v_mov_b32_e32 v101, 0
	s_mov_b32 s41, 0
	v_lshlrev_b32_e32 v135, 6, v146
	v_lshrrev_b32_e32 v147, 2, v146
	v_add_u32_e32 v186, s4, v1
	v_or_b32_e32 v99, 3, v1
	v_or_b32_e32 v104, 2, v1
	v_or_b32_e32 v103, 9, v1
	v_or_b32_e32 v106, 8, v1
	v_or_b32_e32 v105, 11, v1
	v_or_b32_e32 v108, 10, v1
	v_or_b32_e32 v107, 17, v1
	v_or_b32_e32 v110, 16, v1
	v_or_b32_e32 v109, 19, v1
	v_or_b32_e32 v112, 18, v1
	v_or_b32_e32 v111, 25, v1
	v_or_b32_e32 v114, 24, v1
	v_or_b32_e32 v113, 27, v1
	v_or_b32_e32 v116, 26, v1
	v_or_b32_e32 v115, 33, v1
	v_or_b32_e32 v118, 32, v1
	v_or_b32_e32 v117, 35, v1
	v_or_b32_e32 v120, 34, v1
	v_or_b32_e32 v119, 41, v1
	v_or_b32_e32 v122, 40, v1
	v_or_b32_e32 v121, 43, v1
	v_or_b32_e32 v124, 42, v1
	v_or_b32_e32 v123, 49, v1
	v_or_b32_e32 v126, 48, v1
	v_or_b32_e32 v125, 51, v1
	v_or_b32_e32 v128, 50, v1
	v_or_b32_e32 v127, 57, v1
	v_or_b32_e32 v130, 56, v1
	v_or_b32_e32 v129, 59, v1
	v_or_b32_e32 v132, 58, v1
	v_cmp_gt_u32_e64 s[42:43], 32, v146
	v_cmp_eq_u32_e64 s[4:5], 16, v98
	v_cmp_eq_u32_e64 s[6:7], 0, v98
	s_movk_i32 s60, 0x84
	v_and_b32_e32 v134, 32, v184
	v_lshl_add_u32 v229, v45, 2, s10
	v_lshl_add_u32 v231, v47, 2, s10
	v_mul_u32_u24_e32 v232, 0x90, v98
	v_mov_b32_e32 v131, v98
	v_add_u32_e32 v234, 0, v44
	v_lshlrev_b32_e32 v136, 1, v102
	s_movk_i32 s63, 0x60
	s_mov_b64 s[44:45], 0x100000
	s_mov_b64 s[46:47], 0x2000
	s_mov_b64 s[48:49], 0x102000
	s_mov_b64 s[50:51], 0x1000000
	s_mov_b32 s64, 0xff800000
	s_mov_b32 s65, 0x41800000
	s_mov_b32 s66, 0xc1800000
	s_movk_i32 s67, 0xff80
	s_add_i32 s68, 0, 0x1a900
	s_add_i32 s69, 0, 0x1a804
	s_add_i32 s70, 0, 0x1a808
	s_add_i32 s71, 0, 0x1a80c
	v_lshlrev_b32_e32 v140, 1, v36
	v_lshlrev_b32_e32 v142, 1, v38
	v_lshlrev_b32_e32 v144, 1, v40
	v_lshlrev_b32_e32 v148, 1, v42
	v_mov_b32_e32 v235, 0x60
	v_add_u32_e32 v236, v37, v188
	v_mov_b32_e32 v237, 0xff800000
	v_add_u32_e32 v238, v39, v191
	v_mbcnt_hi_u32_b32 v239, -1, v34
	v_add_u32_e32 v240, v41, v43
	v_mov_b32_e32 v241, 0x461c4000
	s_branch .LBB0_738

; __global__ void __launch_bounds__(512, 2) mk_fwd(Args args) {
	.amdhsa_kernel _Z6mk_fwd4Args
		.amdhsa_group_segment_fixed_size 0
		.amdhsa_private_segment_fixed_size 0
		.amdhsa_kernarg_size 464
		.amdhsa_user_sgpr_count 2
		.amdhsa_user_sgpr_dispatch_ptr 0
		.amdhsa_user_sgpr_queue_ptr 0
		.amdhsa_user_sgpr_kernarg_segment_ptr 1
		.amdhsa_user_sgpr_dispatch_id 0
		.amdhsa_user_sgpr_kernarg_preload_length 0
		.amdhsa_user_sgpr_kernarg_preload_offset 0
		.amdhsa_user_sgpr_private_segment_size 0
		.amdhsa_uses_dynamic_stack 0
		.amdhsa_enable_private_segment 0
		.amdhsa_system_sgpr_workgroup_id_x 1
		.amdhsa_system_sgpr_workgroup_id_y 0
		.amdhsa_system_sgpr_workgroup_id_z 0
		.amdhsa_system_sgpr_workgroup_info 0
		.amdhsa_system_vgpr_workitem_id 2
		.amdhsa_next_free_vgpr 256
		.amdhsa_next_free_sgpr 102
		.amdhsa_accum_offset 256
		.amdhsa_reserve_vcc 1
		.amdhsa_float_round_mode_32 0
		.amdhsa_float_round_mode_16_64 0
		.amdhsa_float_denorm_mode_32 3
		.amdhsa_float_denorm_mode_16_64 3
		.amdhsa_dx10_clamp 1
		.amdhsa_ieee_mode 1
		.amdhsa_fp16_overflow 0
		.amdhsa_tg_split 0
		.amdhsa_exception_fp_ieee_invalid_op 0
		.amdhsa_exception_fp_denorm_src 0
		.amdhsa_exception_fp_ieee_div_zero 0
		.amdhsa_exception_fp_ieee_overflow 0
		.amdhsa_exception_fp_ieee_underflow 0
		.amdhsa_exception_fp_ieee_inexact 0
		.amdhsa_exception_int_div_zero 0
	.end_amdhsa_kernel

; __global__ void __launch_bounds__(512, 2) mk_fwd(Args args) {
amdhsa.kernels:
  - .agpr_count:     0
    .args:
      - .offset:         0
        .size:           208
        .value_kind:     by_value
      - .offset:         208
        .size:           4
        .value_kind:     hidden_block_count_x
      - .offset:         212
        .size:           4
        .value_kind:     hidden_block_count_y
      - .offset:         216
        .size:           4
        .value_kind:     hidden_block_count_z
      - .offset:         220
        .size:           2
        .value_kind:     hidden_group_size_x
      - .offset:         222
        .size:           2
        .value_kind:     hidden_group_size_y
      - .offset:         224
        .size:           2
        .value_kind:     hidden_group_size_z
      - .offset:         226
        .size:           2
        .value_kind:     hidden_remainder_x
      - .offset:         228
        .size:           2
        .value_kind:     hidden_remainder_y
      - .offset:         230
        .size:           2
        .value_kind:     hidden_remainder_z
      - .offset:         248
        .size:           8
        .value_kind:     hidden_global_offset_x
      - .offset:         256
        .size:           8
        .value_kind:     hidden_global_offset_y
      - .offset:         264
        .size:           8
        .value_kind:     hidden_global_offset_z
      - .offset:         272
        .size:           2
        .value_kind:     hidden_grid_dims
      - .offset:         296
        .size:           8
        .value_kind:     hidden_multigrid_sync_arg
      - .offset:         328
        .size:           4
        .value_kind:     hidden_dynamic_lds_size
    .group_segment_fixed_size: 0
    .kernarg_segment_align: 8
    .kernarg_segment_size: 464
    .language:       OpenCL C
    .language_version:
      - 2
      - 0
    .max_flat_workgroup_size: 512
    .name:           _Z6mk_fwd4Args
    .private_segment_fixed_size: 0
    .sgpr_count:     108
    .sgpr_spill_count: 0
    .symbol:         _Z6mk_fwd4Args.kd
    .uniform_work_group_size: 1
    .uses_dynamic_stack: false
    .vgpr_count:     256
    .vgpr_spill_count: 0
    .wavefront_size: 64
